# QKV and SwiGLU epilogues: bf16 output quads lane-transposed with ds_bpermute so 4 consecutive lanes store 64 contiguous bytes (coalesced stores); QKV epilogue hand-batched
# speedup vs baseline: 1.0151x; 1.0151x over previous
;     __device__ __forceinline__ void operator()(AccRef acc, const pg8::Unit& u, int wr, int wc, int fr, int fq) const {
;     ...
;         bf16* dst = (bf16*)(big + off) + lg * 64 + 8 * fq;
;         f32x4 gv[2][2];
; #pragma unroll
;         for (int bj = 0; bj < 2; ++bj)
; #pragma unroll
;             for (int n = 0; n < 2; ++n) {
;                 f32x4 g4 = {1.f, 1.f, 1.f, 1.f};
;                 if (gain) g4 = *(const f32x4*)(gain + 32 * bj + 8 * fq + 4 * n);
;                 gv[bj][n] = g4 * sc;
;             }
; #pragma unroll
;         for (int ai = 0; ai < 2; ++ai)
; #pragma unroll
;             for (int m = 0; m < 4; ++m) {
;                 const int row = row0 + ai * 128 + m * 16;
;                 const float rsr = rst[row & 255];
;                 f32x4 xv[2][2];
; #pragma unroll
;                 for (int bj = 0; bj < 2; ++bj)
; #pragma unroll
;                     for (int n = 0; n < 2; ++n) xv[bj][n] = acc[ai][bj][m][n] * rsr;
.Lqkv_head:
	v_lshlrev_b32_e32 v21, 2, v19
	v_add_u32_e32 v21, 0x20100, v21
	ds_read_b32 v48, v21 offset:0
	ds_read_b32 v50, v21 offset:64
	ds_read_b32 v52, v21 offset:128
	ds_read_b32 v54, v21 offset:192
	ds_read_b32 v56, v21 offset:512
	ds_read_b32 v58, v21 offset:576
	ds_read_b32 v60, v21 offset:640
	ds_read_b32 v62, v21 offset:704
	s_lshl_b32 s20, s45, 8
	s_add_i32 s20, s20, s71
	v_lshrrev_b32_e32 v23, 2, v236
	v_add_u32_e32 v22, s20, v23
	v_mul_lo_u32 v22, v22, s10
	v_and_b32_e32 v43, 3, v236
	v_lshlrev_b32_e32 v20, 4, v43
	v_lshl_add_u32 v22, v22, 1, v20
	v_lshlrev_b32_e32 v43, 6, v43
	v_lshl_or_b32 v43, v23, 2, v43
	v_readlane_b32 s20, v255, 23
	v_readlane_b32 s21, v255, 24
	s_add_u32 s12, s12, s20
	s_addc_u32 s13, s13, s21
	s_lshl_b32 s20, s30, 7
	s_add_u32 s12, s12, s20
	s_addc_u32 s13, s13, 0
	s_lshl_b32 s20, s10, 5
	s_mul_i32 s21, s20, 5
	s_mov_b32 s3, 0x800000
	v_and_b32_e32 v41, 64, v236
	v_xor_b32_e32 v40, 16, v236
	v_add_u32_e32 v41, 64, v41
	v_xor_b32_e32 v42, 32, v236
	v_cmp_lt_i32_e32 vcc, v40, v41
	v_cmp_lt_i32_e64 s[6:7], v42, v41
	s_nop 1
	v_cndmask_b32_e32 v40, v236, v40, vcc
	v_cndmask_b32_e64 v42, v236, v42, s[6:7]
	v_lshlrev_b32_e32 v40, 2, v40
	v_lshlrev_b32_e32 v42, 2, v42
	s_waitcnt lgkmcnt(7)
	v_pk_mul_f32 v[190:191], v[190:191], v[48:49] op_sel_hi:[1,0]
	v_pk_mul_f32 v[192:193], v[192:193], v[48:49] op_sel_hi:[1,0]
	v_pk_mul_f32 v[186:187], v[186:187], v[48:49] op_sel_hi:[1,0]
	v_pk_mul_f32 v[188:189], v[188:189], v[48:49] op_sel_hi:[1,0]
	v_pk_mul_f32 v[182:183], v[182:183], v[48:49] op_sel_hi:[1,0]
	v_pk_mul_f32 v[184:185], v[184:185], v[48:49] op_sel_hi:[1,0]
	v_pk_mul_f32 v[178:179], v[178:179], v[48:49] op_sel_hi:[1,0]
	v_pk_mul_f32 v[180:181], v[180:181], v[48:49] op_sel_hi:[1,0]
	s_waitcnt lgkmcnt(6)
	v_pk_mul_f32 v[174:175], v[174:175], v[50:51] op_sel_hi:[1,0]
	v_pk_mul_f32 v[176:177], v[176:177], v[50:51] op_sel_hi:[1,0]
	v_pk_mul_f32 v[170:171], v[170:171], v[50:51] op_sel_hi:[1,0]
	v_pk_mul_f32 v[172:173], v[172:173], v[50:51] op_sel_hi:[1,0]
	v_pk_mul_f32 v[166:167], v[166:167], v[50:51] op_sel_hi:[1,0]
	v_pk_mul_f32 v[168:169], v[168:169], v[50:51] op_sel_hi:[1,0]
	v_pk_mul_f32 v[162:163], v[162:163], v[50:51] op_sel_hi:[1,0]
	v_pk_mul_f32 v[164:165], v[164:165], v[50:51] op_sel_hi:[1,0]
	s_waitcnt lgkmcnt(5)
	v_pk_mul_f32 v[158:159], v[158:159], v[52:53] op_sel_hi:[1,0]
	v_pk_mul_f32 v[160:161], v[160:161], v[52:53] op_sel_hi:[1,0]
	v_pk_mul_f32 v[154:155], v[154:155], v[52:53] op_sel_hi:[1,0]
	v_pk_mul_f32 v[156:157], v[156:157], v[52:53] op_sel_hi:[1,0]
	v_pk_mul_f32 v[150:151], v[150:151], v[52:53] op_sel_hi:[1,0]
	v_pk_mul_f32 v[152:153], v[152:153], v[52:53] op_sel_hi:[1,0]
	v_pk_mul_f32 v[146:147], v[146:147], v[52:53] op_sel_hi:[1,0]
	v_pk_mul_f32 v[148:149], v[148:149], v[52:53] op_sel_hi:[1,0]
	s_waitcnt lgkmcnt(4)
	v_pk_mul_f32 v[142:143], v[142:143], v[54:55] op_sel_hi:[1,0]
	v_pk_mul_f32 v[144:145], v[144:145], v[54:55] op_sel_hi:[1,0]
	v_pk_mul_f32 v[138:139], v[138:139], v[54:55] op_sel_hi:[1,0]
	v_pk_mul_f32 v[140:141], v[140:141], v[54:55] op_sel_hi:[1,0]
	v_pk_mul_f32 v[134:135], v[134:135], v[54:55] op_sel_hi:[1,0]
	v_pk_mul_f32 v[136:137], v[136:137], v[54:55] op_sel_hi:[1,0]
	v_pk_mul_f32 v[130:131], v[130:131], v[54:55] op_sel_hi:[1,0]
	v_pk_mul_f32 v[132:133], v[132:133], v[54:55] op_sel_hi:[1,0]
	s_waitcnt lgkmcnt(3)
	v_pk_mul_f32 v[126:127], v[126:127], v[56:57] op_sel_hi:[1,0]
	v_pk_mul_f32 v[128:129], v[128:129], v[56:57] op_sel_hi:[1,0]
	v_pk_mul_f32 v[122:123], v[122:123], v[56:57] op_sel_hi:[1,0]
	v_pk_mul_f32 v[124:125], v[124:125], v[56:57] op_sel_hi:[1,0]
	v_pk_mul_f32 v[118:119], v[118:119], v[56:57] op_sel_hi:[1,0]
	v_pk_mul_f32 v[120:121], v[120:121], v[56:57] op_sel_hi:[1,0]
	v_pk_mul_f32 v[114:115], v[114:115], v[56:57] op_sel_hi:[1,0]
	v_pk_mul_f32 v[116:117], v[116:117], v[56:57] op_sel_hi:[1,0]
	s_waitcnt lgkmcnt(2)
	v_pk_mul_f32 v[110:111], v[110:111], v[58:59] op_sel_hi:[1,0]
	v_pk_mul_f32 v[112:113], v[112:113], v[58:59] op_sel_hi:[1,0]
	v_pk_mul_f32 v[106:107], v[106:107], v[58:59] op_sel_hi:[1,0]
	v_pk_mul_f32 v[108:109], v[108:109], v[58:59] op_sel_hi:[1,0]
	v_pk_mul_f32 v[102:103], v[102:103], v[58:59] op_sel_hi:[1,0]
	v_pk_mul_f32 v[104:105], v[104:105], v[58:59] op_sel_hi:[1,0]
	v_pk_mul_f32 v[98:99], v[98:99], v[58:59] op_sel_hi:[1,0]
	v_pk_mul_f32 v[100:101], v[100:101], v[58:59] op_sel_hi:[1,0]
	s_waitcnt lgkmcnt(1)
	v_pk_mul_f32 v[94:95], v[94:95], v[60:61] op_sel_hi:[1,0]
	v_pk_mul_f32 v[96:97], v[96:97], v[60:61] op_sel_hi:[1,0]
	v_pk_mul_f32 v[90:91], v[90:91], v[60:61] op_sel_hi:[1,0]
	v_pk_mul_f32 v[92:93], v[92:93], v[60:61] op_sel_hi:[1,0]
	v_pk_mul_f32 v[86:87], v[86:87], v[60:61] op_sel_hi:[1,0]
	v_pk_mul_f32 v[88:89], v[88:89], v[60:61] op_sel_hi:[1,0]
	v_pk_mul_f32 v[82:83], v[82:83], v[60:61] op_sel_hi:[1,0]
	v_pk_mul_f32 v[84:85], v[84:85], v[60:61] op_sel_hi:[1,0]
	s_waitcnt lgkmcnt(0)
	v_pk_mul_f32 v[78:79], v[78:79], v[62:63] op_sel_hi:[1,0]
	v_pk_mul_f32 v[80:81], v[80:81], v[62:63] op_sel_hi:[1,0]
	v_pk_mul_f32 v[74:75], v[74:75], v[62:63] op_sel_hi:[1,0]
	v_pk_mul_f32 v[76:77], v[76:77], v[62:63] op_sel_hi:[1,0]
	v_pk_mul_f32 v[70:71], v[70:71], v[62:63] op_sel_hi:[1,0]
	v_pk_mul_f32 v[72:73], v[72:73], v[62:63] op_sel_hi:[1,0]
	v_pk_mul_f32 v[66:67], v[66:67], v[62:63] op_sel_hi:[1,0]
	v_pk_mul_f32 v[68:69], v[68:69], v[62:63] op_sel_hi:[1,0]
	s_cmp_eq_u64 s[22:23], 0
	s_cbranch_scc1 .Lqkv_plain
;     __device__ __forceinline__ void operator()(AccRef acc, const pg8::Unit& u, int wr, int wc, int fr, int fq) const {
;     ...
;                 float rs = 1.f;
;                 if (gain) {
;                     float ss = 0.f;
; #pragma unroll
;                     for (int bj = 0; bj < 2; ++bj)
; #pragma unroll
;                         for (int n = 0; n < 2; ++n) { const f32x4 x = xv[bj][n]; ss += (x[0] * x[0] + x[1] * x[1]) + (x[2] * x[2] + x[3] * x[3]); }
;                     ss += __shfl_xor(ss, 16); ss += __shfl_xor(ss, 32);
;                     rs = rsqrtf(ss * (1.0f / 64.0f) + RMS_EPS);
;                 }
	v_pk_mul_f32 v[24:25], v[190:191], v[190:191]
	v_pk_mul_f32 v[26:27], v[174:175], v[174:175]
	v_pk_mul_f32 v[28:29], v[158:159], v[158:159]
	v_pk_mul_f32 v[30:31], v[142:143], v[142:143]
	v_pk_mul_f32 v[32:33], v[126:127], v[126:127]
	v_pk_mul_f32 v[34:35], v[110:111], v[110:111]
	v_pk_mul_f32 v[36:37], v[94:95], v[94:95]
	v_pk_mul_f32 v[38:39], v[78:79], v[78:79]
	v_pk_fma_f32 v[24:25], v[192:193], v[192:193], v[24:25]
	v_pk_fma_f32 v[26:27], v[176:177], v[176:177], v[26:27]
	v_pk_fma_f32 v[28:29], v[160:161], v[160:161], v[28:29]
	v_pk_fma_f32 v[30:31], v[144:145], v[144:145], v[30:31]
	v_pk_fma_f32 v[32:33], v[128:129], v[128:129], v[32:33]
	v_pk_fma_f32 v[34:35], v[112:113], v[112:113], v[34:35]
	v_pk_fma_f32 v[36:37], v[96:97], v[96:97], v[36:37]
	v_pk_fma_f32 v[38:39], v[80:81], v[80:81], v[38:39]
	v_pk_fma_f32 v[24:25], v[186:187], v[186:187], v[24:25]
	v_pk_fma_f32 v[26:27], v[170:171], v[170:171], v[26:27]
	v_pk_fma_f32 v[28:29], v[154:155], v[154:155], v[28:29]
	v_pk_fma_f32 v[30:31], v[138:139], v[138:139], v[30:31]
	v_pk_fma_f32 v[32:33], v[122:123], v[122:123], v[32:33]
	v_pk_fma_f32 v[34:35], v[106:107], v[106:107], v[34:35]
	v_pk_fma_f32 v[36:37], v[90:91], v[90:91], v[36:37]
	v_pk_fma_f32 v[38:39], v[74:75], v[74:75], v[38:39]
	v_pk_fma_f32 v[24:25], v[188:189], v[188:189], v[24:25]
	v_pk_fma_f32 v[26:27], v[172:173], v[172:173], v[26:27]
	v_pk_fma_f32 v[28:29], v[156:157], v[156:157], v[28:29]
	v_pk_fma_f32 v[30:31], v[140:141], v[140:141], v[30:31]
	v_pk_fma_f32 v[32:33], v[124:125], v[124:125], v[32:33]
	v_pk_fma_f32 v[34:35], v[108:109], v[108:109], v[34:35]
	v_pk_fma_f32 v[36:37], v[92:93], v[92:93], v[36:37]
	v_pk_fma_f32 v[38:39], v[76:77], v[76:77], v[38:39]
	v_pk_fma_f32 v[24:25], v[182:183], v[182:183], v[24:25]
	v_pk_fma_f32 v[26:27], v[166:167], v[166:167], v[26:27]
	v_pk_fma_f32 v[28:29], v[150:151], v[150:151], v[28:29]
	v_pk_fma_f32 v[30:31], v[134:135], v[134:135], v[30:31]
	v_pk_fma_f32 v[32:33], v[118:119], v[118:119], v[32:33]
	v_pk_fma_f32 v[34:35], v[102:103], v[102:103], v[34:35]
	v_pk_fma_f32 v[36:37], v[86:87], v[86:87], v[36:37]
	v_pk_fma_f32 v[38:39], v[70:71], v[70:71], v[38:39]
	v_pk_fma_f32 v[24:25], v[184:185], v[184:185], v[24:25]
	v_pk_fma_f32 v[26:27], v[168:169], v[168:169], v[26:27]
	v_pk_fma_f32 v[28:29], v[152:153], v[152:153], v[28:29]
	v_pk_fma_f32 v[30:31], v[136:137], v[136:137], v[30:31]
	v_pk_fma_f32 v[32:33], v[120:121], v[120:121], v[32:33]
	v_pk_fma_f32 v[34:35], v[104:105], v[104:105], v[34:35]
	v_pk_fma_f32 v[36:37], v[88:89], v[88:89], v[36:37]
	v_pk_fma_f32 v[38:39], v[72:73], v[72:73], v[38:39]
	v_pk_fma_f32 v[24:25], v[178:179], v[178:179], v[24:25]
	v_pk_fma_f32 v[26:27], v[162:163], v[162:163], v[26:27]
	v_pk_fma_f32 v[28:29], v[146:147], v[146:147], v[28:29]
	v_pk_fma_f32 v[30:31], v[130:131], v[130:131], v[30:31]
	v_pk_fma_f32 v[32:33], v[114:115], v[114:115], v[32:33]
	v_pk_fma_f32 v[34:35], v[98:99], v[98:99], v[34:35]
	v_pk_fma_f32 v[36:37], v[82:83], v[82:83], v[36:37]
	v_pk_fma_f32 v[38:39], v[66:67], v[66:67], v[38:39]
	v_pk_fma_f32 v[24:25], v[180:181], v[180:181], v[24:25]
	v_pk_fma_f32 v[26:27], v[164:165], v[164:165], v[26:27]
	v_pk_fma_f32 v[28:29], v[148:149], v[148:149], v[28:29]
	v_pk_fma_f32 v[30:31], v[132:133], v[132:133], v[30:31]
	v_pk_fma_f32 v[32:33], v[116:117], v[116:117], v[32:33]
	v_pk_fma_f32 v[34:35], v[100:101], v[100:101], v[34:35]
	v_pk_fma_f32 v[36:37], v[84:85], v[84:85], v[36:37]
	v_pk_fma_f32 v[38:39], v[68:69], v[68:69], v[38:39]
	v_add_f32_e32 v49, v24, v25
	v_add_f32_e32 v51, v26, v27
	v_add_f32_e32 v53, v28, v29
	v_add_f32_e32 v55, v30, v31
	v_add_f32_e32 v57, v32, v33
	v_add_f32_e32 v59, v34, v35
	v_add_f32_e32 v61, v36, v37
	v_add_f32_e32 v63, v38, v39
	ds_bpermute_b32 v194, v40, v49
	ds_bpermute_b32 v195, v40, v51
	ds_bpermute_b32 v196, v40, v53
	ds_bpermute_b32 v197, v40, v55
	ds_bpermute_b32 v198, v40, v57
	ds_bpermute_b32 v199, v40, v59
	ds_bpermute_b32 v200, v40, v61
	ds_bpermute_b32 v201, v40, v63
	s_waitcnt lgkmcnt(7)
	v_add_f32_e32 v49, v49, v194
	ds_bpermute_b32 v202, v42, v49
	s_waitcnt lgkmcnt(7)
	v_add_f32_e32 v51, v51, v195
	ds_bpermute_b32 v203, v42, v51
	s_waitcnt lgkmcnt(7)
	v_add_f32_e32 v53, v53, v196
	ds_bpermute_b32 v204, v42, v53
	s_waitcnt lgkmcnt(7)
	v_add_f32_e32 v55, v55, v197
	ds_bpermute_b32 v205, v42, v55
	s_waitcnt lgkmcnt(7)
	v_add_f32_e32 v57, v57, v198
	ds_bpermute_b32 v206, v42, v57
	s_waitcnt lgkmcnt(7)
	v_add_f32_e32 v59, v59, v199
	ds_bpermute_b32 v207, v42, v59
	s_waitcnt lgkmcnt(7)
	v_add_f32_e32 v61, v61, v200
	ds_bpermute_b32 v208, v42, v61
	s_waitcnt lgkmcnt(7)
	v_add_f32_e32 v63, v63, v201
	ds_bpermute_b32 v209, v42, v63
	s_waitcnt vmcnt(0)
	v_pk_mul_f32 v[8:9], s[14:15], v[8:9] op_sel_hi:[0,1]
	v_pk_mul_f32 v[6:7], s[14:15], v[6:7] op_sel_hi:[0,1]
	v_pk_mul_f32 v[4:5], s[14:15], v[4:5] op_sel_hi:[0,1]
	v_pk_mul_f32 v[2:3], s[14:15], v[2:3] op_sel_hi:[0,1]
	v_pk_mul_f32 v[16:17], s[14:15], v[16:17] op_sel_hi:[0,1]
	v_pk_mul_f32 v[10:11], s[14:15], v[10:11] op_sel_hi:[0,1]
	v_pk_mul_f32 v[14:15], s[14:15], v[14:15] op_sel_hi:[0,1]
	v_pk_mul_f32 v[12:13], s[14:15], v[12:13] op_sel_hi:[0,1]
	s_waitcnt lgkmcnt(7)
	v_add_f32_e32 v49, v49, v202
	v_fmamk_f32 v49, v49, 0x3c800000, v215
	v_mul_f32_e32 v194, 0x4b800000, v49
	v_cmp_gt_f32_e32 vcc, s3, v49
	s_nop 1
	v_cndmask_b32_e32 v49, v49, v194, vcc
	v_rsq_f32_e32 v49, v49
	s_nop 0
	v_mul_f32_e32 v194, 0x45800000, v49
	v_cndmask_b32_e32 v48, v49, v194, vcc
	s_waitcnt lgkmcnt(6)
	v_add_f32_e32 v51, v51, v203
	v_fmamk_f32 v51, v51, 0x3c800000, v215
	v_mul_f32_e32 v195, 0x4b800000, v51
	v_cmp_gt_f32_e32 vcc, s3, v51
	s_nop 1
	v_cndmask_b32_e32 v51, v51, v195, vcc
	v_rsq_f32_e32 v51, v51
	s_nop 0
	v_mul_f32_e32 v195, 0x45800000, v51
	v_cndmask_b32_e32 v50, v51, v195, vcc
	s_waitcnt lgkmcnt(5)
; __device__ __forceinline__ unsigned pk2(float lo, float hi) { f32x2_t v = {lo, hi}; bf16x2_t b = __builtin_convertvector(v, bf16x2_t); return __builtin_bit_cast(unsigned, b); }
;     __device__ __forceinline__ void operator()(AccRef acc, const pg8::Unit& u, int wr, int wc, int fr, int fq) const {
;     ...
;                     ss += __shfl_xor(ss, 16); ss += __shfl_xor(ss, 32);
;                     rs = rsqrtf(ss * (1.0f / 64.0f) + RMS_EPS);
;                 }
; #pragma unroll
;                 for (int bj = 0; bj < 2; ++bj) {
;                     const f32x4 v0 = xv[bj][0] * rs * gv[bj][0], v1 = xv[bj][1] * rs * gv[bj][1];
;                     v4u w; w.x = pk2(v0[0], v0[1]); w.y = pk2(v0[2], v0[3]); w.z = pk2(v1[0], v1[1]); w.w = pk2(v1[2], v1[3]);
;                     *(v4u*)(dst + (size_t)row * pitch + 32 * bj) = w;
;                 }
	v_add_f32_e32 v53, v53, v204
	v_fmamk_f32 v53, v53, 0x3c800000, v215
	v_mul_f32_e32 v196, 0x4b800000, v53
	v_cmp_gt_f32_e32 vcc, s3, v53
	s_nop 1
	v_cndmask_b32_e32 v53, v53, v196, vcc
	v_rsq_f32_e32 v53, v53
	s_nop 0
	v_mul_f32_e32 v196, 0x45800000, v53
	v_cndmask_b32_e32 v52, v53, v196, vcc
	s_waitcnt lgkmcnt(4)
	v_add_f32_e32 v55, v55, v205
	v_fmamk_f32 v55, v55, 0x3c800000, v215
	v_mul_f32_e32 v197, 0x4b800000, v55
	v_cmp_gt_f32_e32 vcc, s3, v55
	s_nop 1
	v_cndmask_b32_e32 v55, v55, v197, vcc
	v_rsq_f32_e32 v55, v55
	s_nop 0
	v_mul_f32_e32 v197, 0x45800000, v55
	v_cndmask_b32_e32 v54, v55, v197, vcc
	s_waitcnt lgkmcnt(3)
	v_add_f32_e32 v57, v57, v206
	v_fmamk_f32 v57, v57, 0x3c800000, v215
	v_mul_f32_e32 v198, 0x4b800000, v57
	v_cmp_gt_f32_e32 vcc, s3, v57
	s_nop 1
	v_cndmask_b32_e32 v57, v57, v198, vcc
	v_rsq_f32_e32 v57, v57
	s_nop 0
	v_mul_f32_e32 v198, 0x45800000, v57
	v_cndmask_b32_e32 v56, v57, v198, vcc
	s_waitcnt lgkmcnt(2)
	v_add_f32_e32 v59, v59, v207
	v_fmamk_f32 v59, v59, 0x3c800000, v215
	v_mul_f32_e32 v199, 0x4b800000, v59
	v_cmp_gt_f32_e32 vcc, s3, v59
	s_nop 1
	v_cndmask_b32_e32 v59, v59, v199, vcc
	v_rsq_f32_e32 v59, v59
	s_nop 0
	v_mul_f32_e32 v199, 0x45800000, v59
	v_cndmask_b32_e32 v58, v59, v199, vcc
	s_waitcnt lgkmcnt(1)
	v_add_f32_e32 v61, v61, v208
	v_fmamk_f32 v61, v61, 0x3c800000, v215
	v_mul_f32_e32 v200, 0x4b800000, v61
	v_cmp_gt_f32_e32 vcc, s3, v61
	s_nop 1
	v_cndmask_b32_e32 v61, v61, v200, vcc
	v_rsq_f32_e32 v61, v61
	s_nop 0
	v_mul_f32_e32 v200, 0x45800000, v61
	v_cndmask_b32_e32 v60, v61, v200, vcc
	s_waitcnt lgkmcnt(0)
	v_add_f32_e32 v63, v63, v209
	v_fmamk_f32 v63, v63, 0x3c800000, v215
	v_mul_f32_e32 v201, 0x4b800000, v63
	v_cmp_gt_f32_e32 vcc, s3, v63
	s_nop 1
	v_cndmask_b32_e32 v63, v63, v201, vcc
	v_rsq_f32_e32 v63, v63
	s_nop 0
	v_mul_f32_e32 v201, 0x45800000, v63
	v_cndmask_b32_e32 v62, v63, v201, vcc
	v_pk_mul_f32 v[190:191], v[190:191], v[48:49] op_sel_hi:[1,0]
	v_pk_mul_f32 v[192:193], v[192:193], v[48:49] op_sel_hi:[1,0]
	v_pk_mul_f32 v[186:187], v[186:187], v[48:49] op_sel_hi:[1,0]
	v_pk_mul_f32 v[188:189], v[188:189], v[48:49] op_sel_hi:[1,0]
	v_pk_mul_f32 v[182:183], v[182:183], v[48:49] op_sel_hi:[1,0]
	v_pk_mul_f32 v[184:185], v[184:185], v[48:49] op_sel_hi:[1,0]
	v_pk_mul_f32 v[178:179], v[178:179], v[48:49] op_sel_hi:[1,0]
	v_pk_mul_f32 v[180:181], v[180:181], v[48:49] op_sel_hi:[1,0]
	v_pk_mul_f32 v[190:191], v[2:3], v[190:191]
	v_pk_mul_f32 v[192:193], v[4:5], v[192:193]
	v_pk_mul_f32 v[186:187], v[6:7], v[186:187]
	v_pk_mul_f32 v[188:189], v[8:9], v[188:189]
	v_pk_mul_f32 v[182:183], v[10:11], v[182:183]
	v_pk_mul_f32 v[184:185], v[12:13], v[184:185]
	v_pk_mul_f32 v[178:179], v[14:15], v[178:179]
	v_pk_mul_f32 v[180:181], v[16:17], v[180:181]
	v_cvt_pk_bf16_f32 v190, v190, v191
	v_cvt_pk_bf16_f32 v191, v192, v193
	v_cvt_pk_bf16_f32 v192, v186, v187
	v_cvt_pk_bf16_f32 v193, v188, v189
	v_cvt_pk_bf16_f32 v182, v182, v183
	v_cvt_pk_bf16_f32 v183, v184, v185
	v_cvt_pk_bf16_f32 v184, v178, v179
	v_cvt_pk_bf16_f32 v185, v180, v181
	ds_bpermute_b32 v194, v43, v190
	ds_bpermute_b32 v195, v43, v191
	ds_bpermute_b32 v196, v43, v192
	ds_bpermute_b32 v197, v43, v193
	ds_bpermute_b32 v198, v43, v182
	ds_bpermute_b32 v199, v43, v183
	ds_bpermute_b32 v200, v43, v184
	ds_bpermute_b32 v201, v43, v185
	v_pk_mul_f32 v[174:175], v[174:175], v[50:51] op_sel_hi:[1,0]
	v_pk_mul_f32 v[176:177], v[176:177], v[50:51] op_sel_hi:[1,0]
	v_pk_mul_f32 v[170:171], v[170:171], v[50:51] op_sel_hi:[1,0]
	v_pk_mul_f32 v[172:173], v[172:173], v[50:51] op_sel_hi:[1,0]
	v_pk_mul_f32 v[166:167], v[166:167], v[50:51] op_sel_hi:[1,0]
	v_pk_mul_f32 v[168:169], v[168:169], v[50:51] op_sel_hi:[1,0]
	v_pk_mul_f32 v[162:163], v[162:163], v[50:51] op_sel_hi:[1,0]
	v_pk_mul_f32 v[164:165], v[164:165], v[50:51] op_sel_hi:[1,0]
	v_pk_mul_f32 v[174:175], v[2:3], v[174:175]
	v_pk_mul_f32 v[176:177], v[4:5], v[176:177]
	v_pk_mul_f32 v[170:171], v[6:7], v[170:171]
	v_pk_mul_f32 v[172:173], v[8:9], v[172:173]
	v_pk_mul_f32 v[166:167], v[10:11], v[166:167]
	v_pk_mul_f32 v[168:169], v[12:13], v[168:169]
	v_pk_mul_f32 v[162:163], v[14:15], v[162:163]
	v_pk_mul_f32 v[164:165], v[16:17], v[164:165]
	v_cvt_pk_bf16_f32 v174, v174, v175
	v_cvt_pk_bf16_f32 v175, v176, v177
	v_cvt_pk_bf16_f32 v176, v170, v171
	v_cvt_pk_bf16_f32 v177, v172, v173
	v_cvt_pk_bf16_f32 v166, v166, v167
	v_cvt_pk_bf16_f32 v167, v168, v169
	v_cvt_pk_bf16_f32 v168, v162, v163
	v_cvt_pk_bf16_f32 v169, v164, v165
	ds_bpermute_b32 v202, v43, v174
	ds_bpermute_b32 v203, v43, v175
	ds_bpermute_b32 v204, v43, v176
	ds_bpermute_b32 v205, v43, v177
	ds_bpermute_b32 v206, v43, v166
	ds_bpermute_b32 v207, v43, v167
	ds_bpermute_b32 v208, v43, v168
	ds_bpermute_b32 v209, v43, v169
	s_waitcnt lgkmcnt(8)
	global_store_dwordx4 v22, v[194:197], s[12:13]
	global_store_dwordx4 v22, v[198:201], s[12:13] offset:64
	s_add_u32 s12, s12, s20
	s_addc_u32 s13, s13, 0
	v_pk_mul_f32 v[158:159], v[158:159], v[52:53] op_sel_hi:[1,0]
	v_pk_mul_f32 v[160:161], v[160:161], v[52:53] op_sel_hi:[1,0]
	v_pk_mul_f32 v[154:155], v[154:155], v[52:53] op_sel_hi:[1,0]
	v_pk_mul_f32 v[156:157], v[156:157], v[52:53] op_sel_hi:[1,0]
	v_pk_mul_f32 v[150:151], v[150:151], v[52:53] op_sel_hi:[1,0]
	v_pk_mul_f32 v[152:153], v[152:153], v[52:53] op_sel_hi:[1,0]
	v_pk_mul_f32 v[146:147], v[146:147], v[52:53] op_sel_hi:[1,0]
	v_pk_mul_f32 v[148:149], v[148:149], v[52:53] op_sel_hi:[1,0]
	v_pk_mul_f32 v[158:159], v[2:3], v[158:159]
	v_pk_mul_f32 v[160:161], v[4:5], v[160:161]
	v_pk_mul_f32 v[154:155], v[6:7], v[154:155]
	v_pk_mul_f32 v[156:157], v[8:9], v[156:157]
	v_pk_mul_f32 v[150:151], v[10:11], v[150:151]
	v_pk_mul_f32 v[152:153], v[12:13], v[152:153]
	v_pk_mul_f32 v[146:147], v[14:15], v[146:147]
	v_pk_mul_f32 v[148:149], v[16:17], v[148:149]
	v_cvt_pk_bf16_f32 v158, v158, v159
	v_cvt_pk_bf16_f32 v159, v160, v161
	v_cvt_pk_bf16_f32 v160, v154, v155
	v_cvt_pk_bf16_f32 v161, v156, v157
	v_cvt_pk_bf16_f32 v150, v150, v151
	v_cvt_pk_bf16_f32 v151, v152, v153
	v_cvt_pk_bf16_f32 v152, v146, v147
	v_cvt_pk_bf16_f32 v153, v148, v149
	ds_bpermute_b32 v194, v43, v158
	ds_bpermute_b32 v195, v43, v159
	ds_bpermute_b32 v196, v43, v160
	ds_bpermute_b32 v197, v43, v161
	ds_bpermute_b32 v198, v43, v150
	ds_bpermute_b32 v199, v43, v151
	ds_bpermute_b32 v200, v43, v152
	ds_bpermute_b32 v201, v43, v153
	s_waitcnt lgkmcnt(8)
; __device__ __forceinline__ unsigned pk2(float lo, float hi) { f32x2_t v = {lo, hi}; bf16x2_t b = __builtin_convertvector(v, bf16x2_t); return __builtin_bit_cast(unsigned, b); }
;     __device__ __forceinline__ void operator()(AccRef acc, const pg8::Unit& u, int wr, int wc, int fr, int fq) const {
;     ...
; #pragma unroll
;                 for (int bj = 0; bj < 2; ++bj) {
;                     const f32x4 v0 = xv[bj][0] * rs * gv[bj][0], v1 = xv[bj][1] * rs * gv[bj][1];
;                     v4u w; w.x = pk2(v0[0], v0[1]); w.y = pk2(v0[2], v0[3]); w.z = pk2(v1[0], v1[1]); w.w = pk2(v1[2], v1[3]);
;                     *(v4u*)(dst + (size_t)row * pitch + 32 * bj) = w;
;                 }
	global_store_dwordx4 v22, v[202:205], s[12:13]
	global_store_dwordx4 v22, v[206:209], s[12:13] offset:64
	s_add_u32 s12, s12, s20
	s_addc_u32 s13, s13, 0
	v_pk_mul_f32 v[142:143], v[142:143], v[54:55] op_sel_hi:[1,0]
	v_pk_mul_f32 v[144:145], v[144:145], v[54:55] op_sel_hi:[1,0]
	v_pk_mul_f32 v[138:139], v[138:139], v[54:55] op_sel_hi:[1,0]
	v_pk_mul_f32 v[140:141], v[140:141], v[54:55] op_sel_hi:[1,0]
	v_pk_mul_f32 v[134:135], v[134:135], v[54:55] op_sel_hi:[1,0]
	v_pk_mul_f32 v[136:137], v[136:137], v[54:55] op_sel_hi:[1,0]
	v_pk_mul_f32 v[130:131], v[130:131], v[54:55] op_sel_hi:[1,0]
	v_pk_mul_f32 v[132:133], v[132:133], v[54:55] op_sel_hi:[1,0]
	v_pk_mul_f32 v[142:143], v[2:3], v[142:143]
	v_pk_mul_f32 v[144:145], v[4:5], v[144:145]
	v_pk_mul_f32 v[138:139], v[6:7], v[138:139]
	v_pk_mul_f32 v[140:141], v[8:9], v[140:141]
	v_pk_mul_f32 v[134:135], v[10:11], v[134:135]
	v_pk_mul_f32 v[136:137], v[12:13], v[136:137]
	v_pk_mul_f32 v[130:131], v[14:15], v[130:131]
	v_pk_mul_f32 v[132:133], v[16:17], v[132:133]
	v_cvt_pk_bf16_f32 v142, v142, v143
	v_cvt_pk_bf16_f32 v143, v144, v145
	v_cvt_pk_bf16_f32 v144, v138, v139
	v_cvt_pk_bf16_f32 v145, v140, v141
	v_cvt_pk_bf16_f32 v134, v134, v135
	v_cvt_pk_bf16_f32 v135, v136, v137
	v_cvt_pk_bf16_f32 v136, v130, v131
	v_cvt_pk_bf16_f32 v137, v132, v133
	ds_bpermute_b32 v202, v43, v142
	ds_bpermute_b32 v203, v43, v143
	ds_bpermute_b32 v204, v43, v144
	ds_bpermute_b32 v205, v43, v145
	ds_bpermute_b32 v206, v43, v134
	ds_bpermute_b32 v207, v43, v135
	ds_bpermute_b32 v208, v43, v136
	ds_bpermute_b32 v209, v43, v137
	s_waitcnt lgkmcnt(8)
	global_store_dwordx4 v22, v[194:197], s[12:13]
	global_store_dwordx4 v22, v[198:201], s[12:13] offset:64
	s_add_u32 s12, s12, s20
	s_addc_u32 s13, s13, 0
	v_pk_mul_f32 v[126:127], v[126:127], v[56:57] op_sel_hi:[1,0]
	v_pk_mul_f32 v[128:129], v[128:129], v[56:57] op_sel_hi:[1,0]
	v_pk_mul_f32 v[122:123], v[122:123], v[56:57] op_sel_hi:[1,0]
	v_pk_mul_f32 v[124:125], v[124:125], v[56:57] op_sel_hi:[1,0]
	v_pk_mul_f32 v[118:119], v[118:119], v[56:57] op_sel_hi:[1,0]
	v_pk_mul_f32 v[120:121], v[120:121], v[56:57] op_sel_hi:[1,0]
	v_pk_mul_f32 v[114:115], v[114:115], v[56:57] op_sel_hi:[1,0]
	v_pk_mul_f32 v[116:117], v[116:117], v[56:57] op_sel_hi:[1,0]
	v_pk_mul_f32 v[126:127], v[2:3], v[126:127]
	v_pk_mul_f32 v[128:129], v[4:5], v[128:129]
	v_pk_mul_f32 v[122:123], v[6:7], v[122:123]
	v_pk_mul_f32 v[124:125], v[8:9], v[124:125]
	v_pk_mul_f32 v[118:119], v[10:11], v[118:119]
	v_pk_mul_f32 v[120:121], v[12:13], v[120:121]
	v_pk_mul_f32 v[114:115], v[14:15], v[114:115]
	v_pk_mul_f32 v[116:117], v[16:17], v[116:117]
	v_cvt_pk_bf16_f32 v126, v126, v127
	v_cvt_pk_bf16_f32 v127, v128, v129
	v_cvt_pk_bf16_f32 v128, v122, v123
	v_cvt_pk_bf16_f32 v129, v124, v125
	v_cvt_pk_bf16_f32 v118, v118, v119
	v_cvt_pk_bf16_f32 v119, v120, v121
	v_cvt_pk_bf16_f32 v120, v114, v115
	v_cvt_pk_bf16_f32 v121, v116, v117
	ds_bpermute_b32 v194, v43, v126
	ds_bpermute_b32 v195, v43, v127
	ds_bpermute_b32 v196, v43, v128
	ds_bpermute_b32 v197, v43, v129
	ds_bpermute_b32 v198, v43, v118
	ds_bpermute_b32 v199, v43, v119
	ds_bpermute_b32 v200, v43, v120
	ds_bpermute_b32 v201, v43, v121
	s_waitcnt lgkmcnt(8)
	global_store_dwordx4 v22, v[202:205], s[12:13]
	global_store_dwordx4 v22, v[206:209], s[12:13] offset:64
	s_add_u32 s12, s12, s21
	s_addc_u32 s13, s13, 0
	v_pk_mul_f32 v[110:111], v[110:111], v[58:59] op_sel_hi:[1,0]
	v_pk_mul_f32 v[112:113], v[112:113], v[58:59] op_sel_hi:[1,0]
	v_pk_mul_f32 v[106:107], v[106:107], v[58:59] op_sel_hi:[1,0]
	v_pk_mul_f32 v[108:109], v[108:109], v[58:59] op_sel_hi:[1,0]
	v_pk_mul_f32 v[102:103], v[102:103], v[58:59] op_sel_hi:[1,0]
	v_pk_mul_f32 v[104:105], v[104:105], v[58:59] op_sel_hi:[1,0]
	v_pk_mul_f32 v[98:99], v[98:99], v[58:59] op_sel_hi:[1,0]
	v_pk_mul_f32 v[100:101], v[100:101], v[58:59] op_sel_hi:[1,0]
	v_pk_mul_f32 v[110:111], v[2:3], v[110:111]
	v_pk_mul_f32 v[112:113], v[4:5], v[112:113]
	v_pk_mul_f32 v[106:107], v[6:7], v[106:107]
	v_pk_mul_f32 v[108:109], v[8:9], v[108:109]
	v_pk_mul_f32 v[102:103], v[10:11], v[102:103]
	v_pk_mul_f32 v[104:105], v[12:13], v[104:105]
	v_pk_mul_f32 v[98:99], v[14:15], v[98:99]
	v_pk_mul_f32 v[100:101], v[16:17], v[100:101]
	v_cvt_pk_bf16_f32 v110, v110, v111
	v_cvt_pk_bf16_f32 v111, v112, v113
	v_cvt_pk_bf16_f32 v112, v106, v107
	v_cvt_pk_bf16_f32 v113, v108, v109
	v_cvt_pk_bf16_f32 v102, v102, v103
	v_cvt_pk_bf16_f32 v103, v104, v105
	v_cvt_pk_bf16_f32 v104, v98, v99
	v_cvt_pk_bf16_f32 v105, v100, v101
	ds_bpermute_b32 v202, v43, v110
	ds_bpermute_b32 v203, v43, v111
	ds_bpermute_b32 v204, v43, v112
	ds_bpermute_b32 v205, v43, v113
	ds_bpermute_b32 v206, v43, v102
	ds_bpermute_b32 v207, v43, v103
	ds_bpermute_b32 v208, v43, v104
	ds_bpermute_b32 v209, v43, v105
	s_waitcnt lgkmcnt(8)
	global_store_dwordx4 v22, v[194:197], s[12:13]
	global_store_dwordx4 v22, v[198:201], s[12:13] offset:64
	s_add_u32 s12, s12, s20
	s_addc_u32 s13, s13, 0
	v_pk_mul_f32 v[94:95], v[94:95], v[60:61] op_sel_hi:[1,0]
	v_pk_mul_f32 v[96:97], v[96:97], v[60:61] op_sel_hi:[1,0]
	v_pk_mul_f32 v[90:91], v[90:91], v[60:61] op_sel_hi:[1,0]
	v_pk_mul_f32 v[92:93], v[92:93], v[60:61] op_sel_hi:[1,0]
	v_pk_mul_f32 v[86:87], v[86:87], v[60:61] op_sel_hi:[1,0]
	v_pk_mul_f32 v[88:89], v[88:89], v[60:61] op_sel_hi:[1,0]
	v_pk_mul_f32 v[82:83], v[82:83], v[60:61] op_sel_hi:[1,0]
	v_pk_mul_f32 v[84:85], v[84:85], v[60:61] op_sel_hi:[1,0]
	v_pk_mul_f32 v[94:95], v[2:3], v[94:95]
	v_pk_mul_f32 v[96:97], v[4:5], v[96:97]
	v_pk_mul_f32 v[90:91], v[6:7], v[90:91]
	v_pk_mul_f32 v[92:93], v[8:9], v[92:93]
	v_pk_mul_f32 v[86:87], v[10:11], v[86:87]
	v_pk_mul_f32 v[88:89], v[12:13], v[88:89]
	v_pk_mul_f32 v[82:83], v[14:15], v[82:83]
	v_pk_mul_f32 v[84:85], v[16:17], v[84:85]
	v_cvt_pk_bf16_f32 v94, v94, v95
	v_cvt_pk_bf16_f32 v95, v96, v97
	v_cvt_pk_bf16_f32 v96, v90, v91
	v_cvt_pk_bf16_f32 v97, v92, v93
	v_cvt_pk_bf16_f32 v86, v86, v87
	v_cvt_pk_bf16_f32 v87, v88, v89
	v_cvt_pk_bf16_f32 v88, v82, v83
	v_cvt_pk_bf16_f32 v89, v84, v85
	ds_bpermute_b32 v194, v43, v94
	ds_bpermute_b32 v195, v43, v95
	ds_bpermute_b32 v196, v43, v96
	ds_bpermute_b32 v197, v43, v97
	ds_bpermute_b32 v198, v43, v86
	ds_bpermute_b32 v199, v43, v87
	ds_bpermute_b32 v200, v43, v88
	ds_bpermute_b32 v201, v43, v89
	s_waitcnt lgkmcnt(8)
; __device__ __forceinline__ unsigned pk2(float lo, float hi) { f32x2_t v = {lo, hi}; bf16x2_t b = __builtin_convertvector(v, bf16x2_t); return __builtin_bit_cast(unsigned, b); }
;     __device__ __forceinline__ void operator()(AccRef acc, const pg8::Unit& u, int wr, int wc, int fr, int fq) const {
;     ...
;         size_t off; int pitch, lg; const float* gain = nullptr; float sc = 1.f;
;         if (G < 8)       { off = B_QA; pitch = 512; lg = G;      gain = aq; sc = QSCALE; }
;         else if (G < 16) { off = B_KA; pitch = 512; lg = G - 8;  gain = ak; }
;         else if (G < 24) { off = B_VA; pitch = 512; lg = G - 16; }
;         else if (G < 30) { off = B_QB; pitch = 384; lg = G - 24; sc = QSCALE; }
;         else if (G < 36) { off = B_KB; pitch = 384; lg = G - 30; }
;         else if (G < 42) { off = B_VB; pitch = 384; lg = G - 36; }
;         else if (G < 48) { off = B_QC; pitch = 384; lg = G - 42; gain = cq; sc = QSCALE; }
;         else if (G < 54) { off = B_KC; pitch = 384; lg = G - 48; gain = ck; }
;         else if (G < 60) { off = B_VC; pitch = 384; lg = G - 54; }
;         else if (G < 66) { off = B_QD; pitch = 384; lg = G - 60; gain = dq; sc = QSCALE; }
;         else if (G < 72) { off = B_KD; pitch = 384; lg = G - 66; gain = dk; }
;         else             { off = B_VD; pitch = 384; lg = G - 72; }
;         bf16* dst = (bf16*)(big + off) + lg * 64 + 8 * fq;
;         f32x4 gv[2][2];
; #pragma unroll
;         for (int bj = 0; bj < 2; ++bj)
; #pragma unroll
;             for (int n = 0; n < 2; ++n) {
;                 f32x4 g4 = {1.f, 1.f, 1.f, 1.f};
;                 if (gain) g4 = *(const f32x4*)(gain + 32 * bj + 8 * fq + 4 * n);
;                 gv[bj][n] = g4 * sc;
;             }
;     ...
; #pragma unroll
;                 for (int bj = 0; bj < 2; ++bj) {
;                     const f32x4 v0 = xv[bj][0] * rs * gv[bj][0], v1 = xv[bj][1] * rs * gv[bj][1];
;                     v4u w; w.x = pk2(v0[0], v0[1]); w.y = pk2(v0[2], v0[3]); w.z = pk2(v1[0], v1[1]); w.w = pk2(v1[2], v1[3]);
;                     *(v4u*)(dst + (size_t)row * pitch + 32 * bj) = w;
;                 }
	global_store_dwordx4 v22, v[202:205], s[12:13]
	global_store_dwordx4 v22, v[206:209], s[12:13] offset:64
	s_add_u32 s12, s12, s20
	s_addc_u32 s13, s13, 0
	v_pk_mul_f32 v[78:79], v[78:79], v[62:63] op_sel_hi:[1,0]
	v_pk_mul_f32 v[80:81], v[80:81], v[62:63] op_sel_hi:[1,0]
	v_pk_mul_f32 v[74:75], v[74:75], v[62:63] op_sel_hi:[1,0]
	v_pk_mul_f32 v[76:77], v[76:77], v[62:63] op_sel_hi:[1,0]
	v_pk_mul_f32 v[70:71], v[70:71], v[62:63] op_sel_hi:[1,0]
	v_pk_mul_f32 v[72:73], v[72:73], v[62:63] op_sel_hi:[1,0]
	v_pk_mul_f32 v[66:67], v[66:67], v[62:63] op_sel_hi:[1,0]
	v_pk_mul_f32 v[68:69], v[68:69], v[62:63] op_sel_hi:[1,0]
	v_pk_mul_f32 v[78:79], v[2:3], v[78:79]
	v_pk_mul_f32 v[80:81], v[4:5], v[80:81]
	v_pk_mul_f32 v[74:75], v[6:7], v[74:75]
	v_pk_mul_f32 v[76:77], v[8:9], v[76:77]
	v_pk_mul_f32 v[70:71], v[10:11], v[70:71]
	v_pk_mul_f32 v[72:73], v[12:13], v[72:73]
	v_pk_mul_f32 v[66:67], v[14:15], v[66:67]
	v_pk_mul_f32 v[68:69], v[16:17], v[68:69]
	v_cvt_pk_bf16_f32 v78, v78, v79
	v_cvt_pk_bf16_f32 v79, v80, v81
	v_cvt_pk_bf16_f32 v80, v74, v75
	v_cvt_pk_bf16_f32 v81, v76, v77
	v_cvt_pk_bf16_f32 v70, v70, v71
	v_cvt_pk_bf16_f32 v71, v72, v73
	v_cvt_pk_bf16_f32 v72, v66, v67
	v_cvt_pk_bf16_f32 v73, v68, v69
	ds_bpermute_b32 v202, v43, v78
	ds_bpermute_b32 v203, v43, v79
	ds_bpermute_b32 v204, v43, v80
	ds_bpermute_b32 v205, v43, v81
	ds_bpermute_b32 v206, v43, v70
	ds_bpermute_b32 v207, v43, v71
	ds_bpermute_b32 v208, v43, v72
	ds_bpermute_b32 v209, v43, v73
	s_waitcnt lgkmcnt(8)
	global_store_dwordx4 v22, v[194:197], s[12:13]
	global_store_dwordx4 v22, v[198:201], s[12:13] offset:64
	s_add_u32 s12, s12, s20
	s_addc_u32 s13, s13, 0
	s_waitcnt lgkmcnt(0)
	global_store_dwordx4 v22, v[202:205], s[12:13]
	global_store_dwordx4 v22, v[206:209], s[12:13] offset:64
	s_branch .Lqkv_done
.Lqkv_plain:
	v_pk_mul_f32 v[190:191], s[14:15], v[190:191] op_sel_hi:[0,1]
	v_pk_mul_f32 v[192:193], s[14:15], v[192:193] op_sel_hi:[0,1]
	v_pk_mul_f32 v[186:187], s[14:15], v[186:187] op_sel_hi:[0,1]
	v_pk_mul_f32 v[188:189], s[14:15], v[188:189] op_sel_hi:[0,1]
	v_pk_mul_f32 v[182:183], s[14:15], v[182:183] op_sel_hi:[0,1]
	v_pk_mul_f32 v[184:185], s[14:15], v[184:185] op_sel_hi:[0,1]
	v_pk_mul_f32 v[178:179], s[14:15], v[178:179] op_sel_hi:[0,1]
	v_pk_mul_f32 v[180:181], s[14:15], v[180:181] op_sel_hi:[0,1]
	v_cvt_pk_bf16_f32 v190, v190, v191
	v_cvt_pk_bf16_f32 v191, v192, v193
	v_cvt_pk_bf16_f32 v192, v186, v187
	v_cvt_pk_bf16_f32 v193, v188, v189
	v_cvt_pk_bf16_f32 v182, v182, v183
	v_cvt_pk_bf16_f32 v183, v184, v185
	v_cvt_pk_bf16_f32 v184, v178, v179
	v_cvt_pk_bf16_f32 v185, v180, v181
	ds_bpermute_b32 v194, v43, v190
	ds_bpermute_b32 v195, v43, v191
	ds_bpermute_b32 v196, v43, v192
	ds_bpermute_b32 v197, v43, v193
	ds_bpermute_b32 v198, v43, v182
	ds_bpermute_b32 v199, v43, v183
	ds_bpermute_b32 v200, v43, v184
	ds_bpermute_b32 v201, v43, v185
	v_pk_mul_f32 v[174:175], s[14:15], v[174:175] op_sel_hi:[0,1]
	v_pk_mul_f32 v[176:177], s[14:15], v[176:177] op_sel_hi:[0,1]
	v_pk_mul_f32 v[170:171], s[14:15], v[170:171] op_sel_hi:[0,1]
	v_pk_mul_f32 v[172:173], s[14:15], v[172:173] op_sel_hi:[0,1]
	v_pk_mul_f32 v[166:167], s[14:15], v[166:167] op_sel_hi:[0,1]
	v_pk_mul_f32 v[168:169], s[14:15], v[168:169] op_sel_hi:[0,1]
	v_pk_mul_f32 v[162:163], s[14:15], v[162:163] op_sel_hi:[0,1]
	v_pk_mul_f32 v[164:165], s[14:15], v[164:165] op_sel_hi:[0,1]
	v_cvt_pk_bf16_f32 v174, v174, v175
	v_cvt_pk_bf16_f32 v175, v176, v177
	v_cvt_pk_bf16_f32 v176, v170, v171
	v_cvt_pk_bf16_f32 v177, v172, v173
	v_cvt_pk_bf16_f32 v166, v166, v167
	v_cvt_pk_bf16_f32 v167, v168, v169
	v_cvt_pk_bf16_f32 v168, v162, v163
	v_cvt_pk_bf16_f32 v169, v164, v165
	ds_bpermute_b32 v202, v43, v174
	ds_bpermute_b32 v203, v43, v175
	ds_bpermute_b32 v204, v43, v176
	ds_bpermute_b32 v205, v43, v177
	ds_bpermute_b32 v206, v43, v166
	ds_bpermute_b32 v207, v43, v167
	ds_bpermute_b32 v208, v43, v168
	ds_bpermute_b32 v209, v43, v169
	s_waitcnt lgkmcnt(8)
	global_store_dwordx4 v22, v[194:197], s[12:13]
	global_store_dwordx4 v22, v[198:201], s[12:13] offset:64
	s_add_u32 s12, s12, s20
	s_addc_u32 s13, s13, 0
	v_pk_mul_f32 v[158:159], s[14:15], v[158:159] op_sel_hi:[0,1]
	v_pk_mul_f32 v[160:161], s[14:15], v[160:161] op_sel_hi:[0,1]
	v_pk_mul_f32 v[154:155], s[14:15], v[154:155] op_sel_hi:[0,1]
	v_pk_mul_f32 v[156:157], s[14:15], v[156:157] op_sel_hi:[0,1]
	v_pk_mul_f32 v[150:151], s[14:15], v[150:151] op_sel_hi:[0,1]
	v_pk_mul_f32 v[152:153], s[14:15], v[152:153] op_sel_hi:[0,1]
	v_pk_mul_f32 v[146:147], s[14:15], v[146:147] op_sel_hi:[0,1]
	v_pk_mul_f32 v[148:149], s[14:15], v[148:149] op_sel_hi:[0,1]
	v_cvt_pk_bf16_f32 v158, v158, v159
	v_cvt_pk_bf16_f32 v159, v160, v161
	v_cvt_pk_bf16_f32 v160, v154, v155
	v_cvt_pk_bf16_f32 v161, v156, v157
	v_cvt_pk_bf16_f32 v150, v150, v151
	v_cvt_pk_bf16_f32 v151, v152, v153
	v_cvt_pk_bf16_f32 v152, v146, v147
	v_cvt_pk_bf16_f32 v153, v148, v149
	ds_bpermute_b32 v194, v43, v158
	ds_bpermute_b32 v195, v43, v159
	ds_bpermute_b32 v196, v43, v160
	ds_bpermute_b32 v197, v43, v161
	ds_bpermute_b32 v198, v43, v150
	ds_bpermute_b32 v199, v43, v151
	ds_bpermute_b32 v200, v43, v152
	ds_bpermute_b32 v201, v43, v153
	s_waitcnt lgkmcnt(8)
; __device__ __forceinline__ unsigned pk2(float lo, float hi) { f32x2_t v = {lo, hi}; bf16x2_t b = __builtin_convertvector(v, bf16x2_t); return __builtin_bit_cast(unsigned, b); }
;     __device__ __forceinline__ void operator()(AccRef acc, const pg8::Unit& u, int wr, int wc, int fr, int fq) const {
;     ...
; #pragma unroll
;                 for (int bj = 0; bj < 2; ++bj) {
;                     const f32x4 v0 = xv[bj][0] * rs * gv[bj][0], v1 = xv[bj][1] * rs * gv[bj][1];
;                     v4u w; w.x = pk2(v0[0], v0[1]); w.y = pk2(v0[2], v0[3]); w.z = pk2(v1[0], v1[1]); w.w = pk2(v1[2], v1[3]);
;                     *(v4u*)(dst + (size_t)row * pitch + 32 * bj) = w;
;                 }
	global_store_dwordx4 v22, v[202:205], s[12:13]
	global_store_dwordx4 v22, v[206:209], s[12:13] offset:64
	s_add_u32 s12, s12, s20
	s_addc_u32 s13, s13, 0
	v_pk_mul_f32 v[142:143], s[14:15], v[142:143] op_sel_hi:[0,1]
	v_pk_mul_f32 v[144:145], s[14:15], v[144:145] op_sel_hi:[0,1]
	v_pk_mul_f32 v[138:139], s[14:15], v[138:139] op_sel_hi:[0,1]
	v_pk_mul_f32 v[140:141], s[14:15], v[140:141] op_sel_hi:[0,1]
	v_pk_mul_f32 v[134:135], s[14:15], v[134:135] op_sel_hi:[0,1]
	v_pk_mul_f32 v[136:137], s[14:15], v[136:137] op_sel_hi:[0,1]
	v_pk_mul_f32 v[130:131], s[14:15], v[130:131] op_sel_hi:[0,1]
	v_pk_mul_f32 v[132:133], s[14:15], v[132:133] op_sel_hi:[0,1]
	v_cvt_pk_bf16_f32 v142, v142, v143
	v_cvt_pk_bf16_f32 v143, v144, v145
	v_cvt_pk_bf16_f32 v144, v138, v139
	v_cvt_pk_bf16_f32 v145, v140, v141
	v_cvt_pk_bf16_f32 v134, v134, v135
	v_cvt_pk_bf16_f32 v135, v136, v137
	v_cvt_pk_bf16_f32 v136, v130, v131
	v_cvt_pk_bf16_f32 v137, v132, v133
	ds_bpermute_b32 v202, v43, v142
	ds_bpermute_b32 v203, v43, v143
	ds_bpermute_b32 v204, v43, v144
	ds_bpermute_b32 v205, v43, v145
	ds_bpermute_b32 v206, v43, v134
	ds_bpermute_b32 v207, v43, v135
	ds_bpermute_b32 v208, v43, v136
	ds_bpermute_b32 v209, v43, v137
	s_waitcnt lgkmcnt(8)
	global_store_dwordx4 v22, v[194:197], s[12:13]
	global_store_dwordx4 v22, v[198:201], s[12:13] offset:64
	s_add_u32 s12, s12, s20
	s_addc_u32 s13, s13, 0
	v_pk_mul_f32 v[126:127], s[14:15], v[126:127] op_sel_hi:[0,1]
	v_pk_mul_f32 v[128:129], s[14:15], v[128:129] op_sel_hi:[0,1]
	v_pk_mul_f32 v[122:123], s[14:15], v[122:123] op_sel_hi:[0,1]
	v_pk_mul_f32 v[124:125], s[14:15], v[124:125] op_sel_hi:[0,1]
	v_pk_mul_f32 v[118:119], s[14:15], v[118:119] op_sel_hi:[0,1]
	v_pk_mul_f32 v[120:121], s[14:15], v[120:121] op_sel_hi:[0,1]
	v_pk_mul_f32 v[114:115], s[14:15], v[114:115] op_sel_hi:[0,1]
	v_pk_mul_f32 v[116:117], s[14:15], v[116:117] op_sel_hi:[0,1]
	v_cvt_pk_bf16_f32 v126, v126, v127
	v_cvt_pk_bf16_f32 v127, v128, v129
	v_cvt_pk_bf16_f32 v128, v122, v123
	v_cvt_pk_bf16_f32 v129, v124, v125
	v_cvt_pk_bf16_f32 v118, v118, v119
	v_cvt_pk_bf16_f32 v119, v120, v121
	v_cvt_pk_bf16_f32 v120, v114, v115
	v_cvt_pk_bf16_f32 v121, v116, v117
	ds_bpermute_b32 v194, v43, v126
	ds_bpermute_b32 v195, v43, v127
	ds_bpermute_b32 v196, v43, v128
	ds_bpermute_b32 v197, v43, v129
	ds_bpermute_b32 v198, v43, v118
	ds_bpermute_b32 v199, v43, v119
	ds_bpermute_b32 v200, v43, v120
	ds_bpermute_b32 v201, v43, v121
	s_waitcnt lgkmcnt(8)
	global_store_dwordx4 v22, v[202:205], s[12:13]
	global_store_dwordx4 v22, v[206:209], s[12:13] offset:64
	s_add_u32 s12, s12, s21
	s_addc_u32 s13, s13, 0
	v_pk_mul_f32 v[110:111], s[14:15], v[110:111] op_sel_hi:[0,1]
	v_pk_mul_f32 v[112:113], s[14:15], v[112:113] op_sel_hi:[0,1]
	v_pk_mul_f32 v[106:107], s[14:15], v[106:107] op_sel_hi:[0,1]
	v_pk_mul_f32 v[108:109], s[14:15], v[108:109] op_sel_hi:[0,1]
	v_pk_mul_f32 v[102:103], s[14:15], v[102:103] op_sel_hi:[0,1]
	v_pk_mul_f32 v[104:105], s[14:15], v[104:105] op_sel_hi:[0,1]
	v_pk_mul_f32 v[98:99], s[14:15], v[98:99] op_sel_hi:[0,1]
	v_pk_mul_f32 v[100:101], s[14:15], v[100:101] op_sel_hi:[0,1]
	v_cvt_pk_bf16_f32 v110, v110, v111
	v_cvt_pk_bf16_f32 v111, v112, v113
	v_cvt_pk_bf16_f32 v112, v106, v107
	v_cvt_pk_bf16_f32 v113, v108, v109
	v_cvt_pk_bf16_f32 v102, v102, v103
	v_cvt_pk_bf16_f32 v103, v104, v105
	v_cvt_pk_bf16_f32 v104, v98, v99
	v_cvt_pk_bf16_f32 v105, v100, v101
	ds_bpermute_b32 v202, v43, v110
	ds_bpermute_b32 v203, v43, v111
	ds_bpermute_b32 v204, v43, v112
	ds_bpermute_b32 v205, v43, v113
	ds_bpermute_b32 v206, v43, v102
	ds_bpermute_b32 v207, v43, v103
	ds_bpermute_b32 v208, v43, v104
	ds_bpermute_b32 v209, v43, v105
	s_waitcnt lgkmcnt(8)
	global_store_dwordx4 v22, v[194:197], s[12:13]
	global_store_dwordx4 v22, v[198:201], s[12:13] offset:64
	s_add_u32 s12, s12, s20
	s_addc_u32 s13, s13, 0
	v_pk_mul_f32 v[94:95], s[14:15], v[94:95] op_sel_hi:[0,1]
	v_pk_mul_f32 v[96:97], s[14:15], v[96:97] op_sel_hi:[0,1]
	v_pk_mul_f32 v[90:91], s[14:15], v[90:91] op_sel_hi:[0,1]
	v_pk_mul_f32 v[92:93], s[14:15], v[92:93] op_sel_hi:[0,1]
	v_pk_mul_f32 v[86:87], s[14:15], v[86:87] op_sel_hi:[0,1]
	v_pk_mul_f32 v[88:89], s[14:15], v[88:89] op_sel_hi:[0,1]
	v_pk_mul_f32 v[82:83], s[14:15], v[82:83] op_sel_hi:[0,1]
	v_pk_mul_f32 v[84:85], s[14:15], v[84:85] op_sel_hi:[0,1]
	v_cvt_pk_bf16_f32 v94, v94, v95
	v_cvt_pk_bf16_f32 v95, v96, v97
	v_cvt_pk_bf16_f32 v96, v90, v91
	v_cvt_pk_bf16_f32 v97, v92, v93
	v_cvt_pk_bf16_f32 v86, v86, v87
	v_cvt_pk_bf16_f32 v87, v88, v89
	v_cvt_pk_bf16_f32 v88, v82, v83
	v_cvt_pk_bf16_f32 v89, v84, v85
	ds_bpermute_b32 v194, v43, v94
	ds_bpermute_b32 v195, v43, v95
	ds_bpermute_b32 v196, v43, v96
	ds_bpermute_b32 v197, v43, v97
	ds_bpermute_b32 v198, v43, v86
	ds_bpermute_b32 v199, v43, v87
	ds_bpermute_b32 v200, v43, v88
	ds_bpermute_b32 v201, v43, v89
	s_waitcnt lgkmcnt(8)
	global_store_dwordx4 v22, v[202:205], s[12:13]
	global_store_dwordx4 v22, v[206:209], s[12:13] offset:64
	s_add_u32 s12, s12, s20
	s_addc_u32 s13, s13, 0
	v_pk_mul_f32 v[78:79], s[14:15], v[78:79] op_sel_hi:[0,1]
	v_pk_mul_f32 v[80:81], s[14:15], v[80:81] op_sel_hi:[0,1]
	v_pk_mul_f32 v[74:75], s[14:15], v[74:75] op_sel_hi:[0,1]
	v_pk_mul_f32 v[76:77], s[14:15], v[76:77] op_sel_hi:[0,1]
	v_pk_mul_f32 v[70:71], s[14:15], v[70:71] op_sel_hi:[0,1]
	v_pk_mul_f32 v[72:73], s[14:15], v[72:73] op_sel_hi:[0,1]
	v_pk_mul_f32 v[66:67], s[14:15], v[66:67] op_sel_hi:[0,1]
	v_pk_mul_f32 v[68:69], s[14:15], v[68:69] op_sel_hi:[0,1]
	v_cvt_pk_bf16_f32 v78, v78, v79
	v_cvt_pk_bf16_f32 v79, v80, v81
	v_cvt_pk_bf16_f32 v80, v74, v75
	v_cvt_pk_bf16_f32 v81, v76, v77
	v_cvt_pk_bf16_f32 v70, v70, v71
	v_cvt_pk_bf16_f32 v71, v72, v73
	v_cvt_pk_bf16_f32 v72, v66, v67
	v_cvt_pk_bf16_f32 v73, v68, v69
	ds_bpermute_b32 v202, v43, v78
	ds_bpermute_b32 v203, v43, v79
	ds_bpermute_b32 v204, v43, v80
	ds_bpermute_b32 v205, v43, v81
	ds_bpermute_b32 v206, v43, v70
	ds_bpermute_b32 v207, v43, v71
	ds_bpermute_b32 v208, v43, v72
	ds_bpermute_b32 v209, v43, v73
	s_waitcnt lgkmcnt(8)
	global_store_dwordx4 v22, v[194:197], s[12:13]
	global_store_dwordx4 v22, v[198:201], s[12:13] offset:64
	s_add_u32 s12, s12, s20
	s_addc_u32 s13, s13, 0
	s_waitcnt lgkmcnt(0)
	global_store_dwordx4 v22, v[202:205], s[12:13]
	global_store_dwordx4 v22, v[206:209], s[12:13] offset:64

; __device__ __forceinline__ unsigned pk2(float lo, float hi) { f32x2_t v = {lo, hi}; bf16x2_t b = __builtin_convertvector(v, bf16x2_t); return __builtin_bit_cast(unsigned, b); }
; __device__ __forceinline__ float sigmoidf_(float x) { return __builtin_amdgcn_rcpf(1.0f + fexp2(-x * LOG2E)); }
;     __device__ __forceinline__ void operator()(AccRef acc, const pg8::Unit& u, int wr, int wc, int fr, int fq) const {
;         const int row0 = u.pm * 256 + wr * 64 + fr, col0 = u.pn * 128 + wc * 32 + 8 * fq;
; #pragma unroll
;         for (int ai = 0; ai < 2; ++ai)
; #pragma unroll
;             for (int m = 0; m < 4; ++m) {
;                 const int row = row0 + ai * 128 + m * 16;
;                 const float rs = rst[row & 255];
;                 float v[8];
; #pragma unroll
;                 for (int n = 0; n < 2; ++n)
; #pragma unroll
;                     for (int j = 0; j < 4; ++j) { const float g = acc[ai][0][m][n][j] * rs, up = acc[ai][1][m][n][j] * rs; v[4 * n + j] = g * sigmoidf_(g) * up; }
;                 v4u w; w.x = pk2(v[0], v[1]); w.y = pk2(v[2], v[3]); w.z = pk2(v[4], v[5]); w.w = pk2(v[6], v[7]);
;                 *(v4u*)(U + (size_t)row * FF + col0) = w;
;             }
.LBB0_260:
	s_and_b64 vcc, exec, s[6:7]
	s_cbranch_vccz .LBB0_377
	v_add_u32_e32 v4, s71, v245
	v_lshl_add_u32 v5, s45, 8, v4
	v_add_u32_e32 v36, 0x90, v5
	s_add_i32 s6, 0, 0x20100
	v_and_b32_e32 v14, 0xff, v36
	v_add_u32_e32 v37, 0xa0, v5
	v_add_u32_e32 v7, 16, v5
	v_add_u32_e32 v9, 32, v5
	v_add_u32_e32 v11, 48, v5
	v_lshl_add_u32 v15, v14, 2, s6
	v_and_b32_e32 v14, 0xff, v37
	v_add_u32_e32 v38, 0xb0, v5
	v_and_b32_e32 v4, 0xff, v4
	v_and_b32_e32 v6, 0xff, v7
	v_and_b32_e32 v8, 0xff, v9
	v_and_b32_e32 v10, 0xff, v11
	v_add_u32_e32 v12, 0x80, v5
	v_lshl_add_u32 v16, v14, 2, s6
	v_and_b32_e32 v14, 0xff, v38
	v_lshl_add_u32 v4, v4, 2, s6
	v_lshl_add_u32 v6, v6, 2, s6
	v_lshl_add_u32 v8, v8, 2, s6
	v_lshl_add_u32 v10, v10, 2, s6
	v_and_b32_e32 v13, 0xff, v12
	v_lshl_add_u32 v17, v14, 2, s6
	v_lshl_add_u32 v13, v13, 2, s6
	ds_read_b32 v14, v4
	ds_read_b32 v18, v6
	ds_read_b32 v20, v8
	ds_read_b32 v22, v10
	ds_read_b32 v10, v13
	ds_read_b32 v8, v15
	ds_read_b32 v6, v16
	ds_read_b32 v4, v17
	v_lshrrev_b32_e32 v40, 2, v236
	v_and_b32_e32 v41, 3, v236
	v_sub_u32_e32 v42, v40, v245
	v_add_u32_e32 v5, v5, v42
	v_add_u32_e32 v7, v7, v42
	v_add_u32_e32 v9, v9, v42
	v_add_u32_e32 v11, v11, v42
	v_add_u32_e32 v12, v12, v42
	v_add_u32_e32 v36, v36, v42
	v_add_u32_e32 v37, v37, v42
	v_add_u32_e32 v38, v38, v42
	v_lshlrev_b32_e32 v43, 6, v41
	v_lshl_or_b32 v43, v40, 2, v43
	s_waitcnt lgkmcnt(0)
	v_pk_mul_f32 v[16:17], v[190:191], v[14:15] op_sel_hi:[1,0]
	s_lshl_b32 s3, s40, 7
	v_mul_f32_e32 v13, 0xbfb8aa3b, v16
	v_mul_f32_e32 v15, 0xbfb8aa3b, v17
	v_exp_f32_e32 v13, v13
	v_exp_f32_e32 v15, v15
	s_or_b32 s3, s3, s67
	v_lshl_add_u32 v2, v41, 3, s3
	v_add_f32_e32 v13, 1.0, v13
	v_pk_mul_f32 v[28:29], v[192:193], v[14:15] op_sel_hi:[1,0]
	v_rcp_f32_e32 v24, v13
	v_pk_mul_f32 v[26:27], v[182:183], v[14:15] op_sel_hi:[1,0]
	v_add_f32_e32 v13, 1.0, v15
	v_mul_f32_e32 v15, 0xbfb8aa3b, v28
	v_exp_f32_e32 v15, v15
	v_mul_f32_e32 v19, 0xbfb8aa3b, v29
	v_exp_f32_e32 v19, v19
	v_rcp_f32_e32 v25, v13
	v_add_f32_e32 v13, 1.0, v15
	v_rcp_f32_e32 v30, v13
	v_add_f32_e32 v13, 1.0, v19
	v_rcp_f32_e32 v31, v13
	v_pk_mul_f32 v[16:17], v[16:17], v[24:25]
	v_pk_mul_f32 v[24:25], v[184:185], v[14:15] op_sel_hi:[1,0]
	v_pk_mul_f32 v[16:17], v[26:27], v[16:17]
	v_pk_mul_f32 v[26:27], v[28:29], v[30:31]
	v_pk_mul_f32 v[28:29], v[186:187], v[14:15] op_sel_hi:[1,0]
	v_pk_mul_f32 v[24:25], v[24:25], v[26:27]
	v_mul_f32_e32 v13, 0xbfb8aa3b, v28
	v_mul_f32_e32 v15, 0xbfb8aa3b, v29
	v_exp_f32_e32 v13, v13
	v_exp_f32_e32 v15, v15
	v_readlane_b32 s6, v255, 23
	v_ashrrev_i32_e32 v3, 31, v2
	v_add_f32_e32 v13, 1.0, v13
	v_pk_mul_f32 v[32:33], v[188:189], v[14:15] op_sel_hi:[1,0]
	v_rcp_f32_e32 v26, v13
	v_pk_mul_f32 v[30:31], v[178:179], v[14:15] op_sel_hi:[1,0]
	v_add_f32_e32 v13, 1.0, v15
	v_mul_f32_e32 v15, 0xbfb8aa3b, v32
	v_exp_f32_e32 v15, v15
	v_mul_f32_e32 v19, 0xbfb8aa3b, v33
	v_exp_f32_e32 v19, v19
	v_rcp_f32_e32 v27, v13
	v_add_f32_e32 v13, 1.0, v15
	v_rcp_f32_e32 v34, v13
	v_add_f32_e32 v13, 1.0, v19
	v_rcp_f32_e32 v35, v13
	v_pk_mul_f32 v[26:27], v[28:29], v[26:27]
	v_readlane_b32 s7, v255, 24
	v_pk_mul_f32 v[26:27], v[30:31], v[26:27]
	v_pk_mul_f32 v[14:15], v[180:181], v[14:15] op_sel_hi:[1,0]
	v_pk_mul_f32 v[28:29], v[32:33], v[34:35]
	v_lshl_add_u64 v[2:3], v[2:3], 1, s[6:7]
	v_pk_mul_f32 v[28:29], v[14:15], v[28:29]
	v_cvt_pk_bf16_f32 v14, v16, v17
	v_cvt_pk_bf16_f32 v16, v26, v27
	s_movk_i32 s3, 0x1600
	v_pk_mul_f32 v[26:27], v[174:175], v[18:19] op_sel_hi:[1,0]
	v_cvt_pk_bf16_f32 v15, v24, v25
	v_mad_i64_i32 v[24:25], s[6:7], v5, s3, v[2:3]
	v_mul_f32_e32 v5, 0xbfb8aa3b, v26
	v_exp_f32_e32 v5, v5
	v_mul_f32_e32 v13, 0xbfb8aa3b, v27
	v_exp_f32_e32 v13, v13
	v_cvt_pk_bf16_f32 v17, v28, v29
	v_mov_b32_e32 v52, v24
	v_mov_b32_e32 v53, v25
	ds_bpermute_b32 v44, v43, v14
	ds_bpermute_b32 v45, v43, v15
	ds_bpermute_b32 v46, v43, v16
	ds_bpermute_b32 v47, v43, v17
	v_add_f32_e32 v5, 1.0, v5
	v_pk_mul_f32 v[24:25], v[176:177], v[18:19] op_sel_hi:[1,0]
	v_rcp_f32_e32 v14, v5
	v_add_f32_e32 v5, 1.0, v13
	v_mul_f32_e32 v13, 0xbfb8aa3b, v24
	v_exp_f32_e32 v13, v13
	v_mul_f32_e32 v15, 0xbfb8aa3b, v25
	v_pk_mul_f32 v[16:17], v[166:167], v[18:19] op_sel_hi:[1,0]
	v_exp_f32_e32 v19, v15
	v_rcp_f32_e32 v15, v5
	v_add_f32_e32 v5, 1.0, v13
	v_rcp_f32_e32 v28, v5
	v_add_f32_e32 v5, 1.0, v19
	v_pk_mul_f32 v[14:15], v[26:27], v[14:15]
	v_pk_mul_f32 v[26:27], v[170:171], v[18:19] op_sel_hi:[1,0]
	v_rcp_f32_e32 v29, v5
	v_mul_f32_e32 v5, 0xbfb8aa3b, v26
	v_exp_f32_e32 v5, v5
	v_mul_f32_e32 v13, 0xbfb8aa3b, v27
	v_exp_f32_e32 v13, v13
	v_pk_mul_f32 v[14:15], v[16:17], v[14:15]
	v_pk_mul_f32 v[16:17], v[168:169], v[18:19] op_sel_hi:[1,0]
	v_pk_mul_f32 v[24:25], v[24:25], v[28:29]
	v_add_f32_e32 v5, 1.0, v5
	v_pk_mul_f32 v[30:31], v[172:173], v[18:19] op_sel_hi:[1,0]
	v_pk_mul_f32 v[16:17], v[16:17], v[24:25]
	v_rcp_f32_e32 v24, v5
	v_add_f32_e32 v5, 1.0, v13
	v_mul_f32_e32 v13, 0xbfb8aa3b, v30
	v_pk_mul_f32 v[28:29], v[162:163], v[18:19] op_sel_hi:[1,0]
	v_exp_f32_e32 v13, v13
	v_mul_f32_e32 v19, 0xbfb8aa3b, v31
	v_exp_f32_e32 v19, v19
	v_rcp_f32_e32 v25, v5
	v_add_f32_e32 v5, 1.0, v13
	v_rcp_f32_e32 v32, v5
	v_add_f32_e32 v5, 1.0, v19
	v_rcp_f32_e32 v33, v5
	v_pk_mul_f32 v[24:25], v[26:27], v[24:25]
	v_pk_mul_f32 v[18:19], v[164:165], v[18:19] op_sel_hi:[1,0]
	v_pk_mul_f32 v[24:25], v[28:29], v[24:25]
	v_pk_mul_f32 v[26:27], v[30:31], v[32:33]
	v_cvt_pk_bf16_f32 v14, v14, v15
	v_cvt_pk_bf16_f32 v15, v16, v17
	v_cvt_pk_bf16_f32 v16, v24, v25
	v_pk_mul_f32 v[24:25], v[158:159], v[20:21] op_sel_hi:[1,0]
	v_pk_mul_f32 v[18:19], v[18:19], v[26:27]
	v_mul_f32_e32 v5, 0xbfb8aa3b, v24
	v_cvt_pk_bf16_f32 v17, v18, v19
	v_mad_i64_i32 v[18:19], s[6:7], v7, s3, v[2:3]
	v_exp_f32_e32 v5, v5
	v_mul_f32_e32 v7, 0xbfb8aa3b, v25
	v_exp_f32_e32 v7, v7
	s_waitcnt lgkmcnt(0)
; __device__ __forceinline__ unsigned pk2(float lo, float hi) { f32x2_t v = {lo, hi}; bf16x2_t b = __builtin_convertvector(v, bf16x2_t); return __builtin_bit_cast(unsigned, b); }
; __device__ __forceinline__ float sigmoidf_(float x) { return __builtin_amdgcn_rcpf(1.0f + fexp2(-x * LOG2E)); }
;     __device__ __forceinline__ void operator()(AccRef acc, const pg8::Unit& u, int wr, int wc, int fr, int fq) const {
;         const int row0 = u.pm * 256 + wr * 64 + fr, col0 = u.pn * 128 + wc * 32 + 8 * fq;
; #pragma unroll
;         for (int ai = 0; ai < 2; ++ai)
; #pragma unroll
;             for (int m = 0; m < 4; ++m) {
;                 const int row = row0 + ai * 128 + m * 16;
;                 const float rs = rst[row & 255];
;                 float v[8];
; #pragma unroll
;                 for (int n = 0; n < 2; ++n)
; #pragma unroll
;                     for (int j = 0; j < 4; ++j) { const float g = acc[ai][0][m][n][j] * rs, up = acc[ai][1][m][n][j] * rs; v[4 * n + j] = g * sigmoidf_(g) * up; }
;                 v4u w; w.x = pk2(v[0], v[1]); w.y = pk2(v[2], v[3]); w.z = pk2(v[4], v[5]); w.w = pk2(v[6], v[7]);
;                 *(v4u*)(U + (size_t)row * FF + col0) = w;
;             }
	global_store_dwordx4 v[52:53], v[44:47], off
	v_mov_b32_e32 v54, v18
	v_mov_b32_e32 v55, v19
	ds_bpermute_b32 v48, v43, v14
	ds_bpermute_b32 v49, v43, v15
	ds_bpermute_b32 v50, v43, v16
	ds_bpermute_b32 v51, v43, v17
	v_add_f32_e32 v5, 1.0, v5
	v_pk_mul_f32 v[18:19], v[160:161], v[20:21] op_sel_hi:[1,0]
	v_rcp_f32_e32 v14, v5
	v_add_f32_e32 v5, 1.0, v7
	v_mul_f32_e32 v7, 0xbfb8aa3b, v18
	v_exp_f32_e32 v7, v7
	v_mul_f32_e32 v13, 0xbfb8aa3b, v19
	v_exp_f32_e32 v13, v13
	v_rcp_f32_e32 v15, v5
	v_add_f32_e32 v5, 1.0, v7
	v_rcp_f32_e32 v26, v5
	v_add_f32_e32 v5, 1.0, v13
	v_pk_mul_f32 v[14:15], v[24:25], v[14:15]
	v_pk_mul_f32 v[24:25], v[154:155], v[20:21] op_sel_hi:[1,0]
	v_rcp_f32_e32 v27, v5
	v_mul_f32_e32 v5, 0xbfb8aa3b, v24
	v_exp_f32_e32 v5, v5
	v_mul_f32_e32 v7, 0xbfb8aa3b, v25
	v_exp_f32_e32 v7, v7
	v_pk_mul_f32 v[16:17], v[150:151], v[20:21] op_sel_hi:[1,0]
	v_pk_mul_f32 v[18:19], v[18:19], v[26:27]
	v_pk_mul_f32 v[14:15], v[16:17], v[14:15]
	v_pk_mul_f32 v[16:17], v[152:153], v[20:21] op_sel_hi:[1,0]
	v_add_f32_e32 v5, 1.0, v5
	v_pk_mul_f32 v[28:29], v[156:157], v[20:21] op_sel_hi:[1,0]
	v_pk_mul_f32 v[16:17], v[16:17], v[18:19]
	v_rcp_f32_e32 v18, v5
	v_add_f32_e32 v5, 1.0, v7
	v_mul_f32_e32 v7, 0xbfb8aa3b, v28
	v_exp_f32_e32 v7, v7
	v_mul_f32_e32 v13, 0xbfb8aa3b, v29
	v_exp_f32_e32 v13, v13
	v_rcp_f32_e32 v19, v5
	v_add_f32_e32 v5, 1.0, v7
	v_rcp_f32_e32 v30, v5
	v_add_f32_e32 v5, 1.0, v13
	v_rcp_f32_e32 v31, v5
	v_pk_mul_f32 v[26:27], v[146:147], v[20:21] op_sel_hi:[1,0]
	v_pk_mul_f32 v[18:19], v[24:25], v[18:19]
	v_pk_mul_f32 v[20:21], v[148:149], v[20:21] op_sel_hi:[1,0]
	v_pk_mul_f32 v[24:25], v[28:29], v[30:31]
	v_cvt_pk_bf16_f32 v14, v14, v15
	v_pk_mul_f32 v[20:21], v[20:21], v[24:25]
	v_cvt_pk_bf16_f32 v15, v16, v17
	v_cvt_pk_bf16_f32 v17, v20, v21
	v_pk_mul_f32 v[20:21], v[142:143], v[22:23] op_sel_hi:[1,0]
	v_pk_mul_f32 v[18:19], v[26:27], v[18:19]
	v_mul_f32_e32 v5, 0xbfb8aa3b, v20
	v_exp_f32_e32 v5, v5
	v_mul_f32_e32 v7, 0xbfb8aa3b, v21
	v_exp_f32_e32 v7, v7
	v_cvt_pk_bf16_f32 v16, v18, v19
	v_mad_i64_i32 v[18:19], s[6:7], v9, s3, v[2:3]
	s_waitcnt lgkmcnt(0)
	global_store_dwordx4 v[54:55], v[48:51], off
	v_mov_b32_e32 v52, v18
	v_mov_b32_e32 v53, v19
	ds_bpermute_b32 v44, v43, v14
	ds_bpermute_b32 v45, v43, v15
	ds_bpermute_b32 v46, v43, v16
	ds_bpermute_b32 v47, v43, v17
	v_add_f32_e32 v5, 1.0, v5
	v_pk_mul_f32 v[18:19], v[144:145], v[22:23] op_sel_hi:[1,0]
	v_rcp_f32_e32 v14, v5
	v_add_f32_e32 v5, 1.0, v7
	v_mul_f32_e32 v7, 0xbfb8aa3b, v18
	v_exp_f32_e32 v7, v7
	v_mul_f32_e32 v9, 0xbfb8aa3b, v19
	v_exp_f32_e32 v9, v9
	v_rcp_f32_e32 v15, v5
	v_add_f32_e32 v5, 1.0, v7
	v_rcp_f32_e32 v24, v5
	v_add_f32_e32 v5, 1.0, v9
	v_pk_mul_f32 v[14:15], v[20:21], v[14:15]
	v_pk_mul_f32 v[20:21], v[138:139], v[22:23] op_sel_hi:[1,0]
	v_rcp_f32_e32 v25, v5
	v_mul_f32_e32 v5, 0xbfb8aa3b, v20
	v_exp_f32_e32 v5, v5
	v_mul_f32_e32 v7, 0xbfb8aa3b, v21
	v_exp_f32_e32 v7, v7
	v_pk_mul_f32 v[16:17], v[134:135], v[22:23] op_sel_hi:[1,0]
	v_pk_mul_f32 v[18:19], v[18:19], v[24:25]
	v_pk_mul_f32 v[14:15], v[16:17], v[14:15]
	v_pk_mul_f32 v[16:17], v[136:137], v[22:23] op_sel_hi:[1,0]
	v_add_f32_e32 v5, 1.0, v5
	v_pk_mul_f32 v[26:27], v[140:141], v[22:23] op_sel_hi:[1,0]
	v_pk_mul_f32 v[16:17], v[16:17], v[18:19]
	v_rcp_f32_e32 v18, v5
	v_add_f32_e32 v5, 1.0, v7
	v_mul_f32_e32 v7, 0xbfb8aa3b, v26
	v_exp_f32_e32 v7, v7
	v_mul_f32_e32 v9, 0xbfb8aa3b, v27
	v_exp_f32_e32 v9, v9
	v_rcp_f32_e32 v19, v5
	v_add_f32_e32 v5, 1.0, v7
	v_rcp_f32_e32 v28, v5
	v_add_f32_e32 v5, 1.0, v9
	v_rcp_f32_e32 v29, v5
	v_pk_mul_f32 v[24:25], v[130:131], v[22:23] op_sel_hi:[1,0]
	v_pk_mul_f32 v[18:19], v[20:21], v[18:19]
	v_pk_mul_f32 v[20:21], v[132:133], v[22:23] op_sel_hi:[1,0]
	v_pk_mul_f32 v[22:23], v[26:27], v[28:29]
	v_cvt_pk_bf16_f32 v14, v14, v15
	v_pk_mul_f32 v[20:21], v[20:21], v[22:23]
	v_cvt_pk_bf16_f32 v15, v16, v17
	v_cvt_pk_bf16_f32 v17, v20, v21
	v_pk_mul_f32 v[20:21], v[126:127], v[10:11] op_sel_hi:[1,0]
	v_pk_mul_f32 v[18:19], v[24:25], v[18:19]
	v_mul_f32_e32 v5, 0xbfb8aa3b, v20
	v_exp_f32_e32 v5, v5
	v_mul_f32_e32 v7, 0xbfb8aa3b, v21
	v_exp_f32_e32 v7, v7
	v_cvt_pk_bf16_f32 v16, v18, v19
	v_mad_i64_i32 v[18:19], s[6:7], v11, s3, v[2:3]
	s_waitcnt lgkmcnt(0)
	global_store_dwordx4 v[52:53], v[44:47], off
	v_mov_b32_e32 v54, v18
	v_mov_b32_e32 v55, v19
	ds_bpermute_b32 v48, v43, v14
	ds_bpermute_b32 v49, v43, v15
	ds_bpermute_b32 v50, v43, v16
	ds_bpermute_b32 v51, v43, v17
	v_add_f32_e32 v5, 1.0, v5
	v_pk_mul_f32 v[18:19], v[128:129], v[10:11] op_sel_hi:[1,0]
	v_rcp_f32_e32 v14, v5
	v_add_f32_e32 v5, 1.0, v7
	v_mul_f32_e32 v7, 0xbfb8aa3b, v18
	v_exp_f32_e32 v7, v7
	v_mul_f32_e32 v9, 0xbfb8aa3b, v19
	v_exp_f32_e32 v9, v9
	v_rcp_f32_e32 v15, v5
	v_add_f32_e32 v5, 1.0, v7
	v_rcp_f32_e32 v22, v5
	v_add_f32_e32 v5, 1.0, v9
	v_pk_mul_f32 v[14:15], v[20:21], v[14:15]
	v_pk_mul_f32 v[20:21], v[122:123], v[10:11] op_sel_hi:[1,0]
	v_rcp_f32_e32 v23, v5
	v_mul_f32_e32 v5, 0xbfb8aa3b, v20
	v_exp_f32_e32 v5, v5
	v_mul_f32_e32 v7, 0xbfb8aa3b, v21
	v_exp_f32_e32 v7, v7
	v_pk_mul_f32 v[16:17], v[118:119], v[10:11] op_sel_hi:[1,0]
	v_pk_mul_f32 v[18:19], v[18:19], v[22:23]
	v_pk_mul_f32 v[14:15], v[16:17], v[14:15]
	v_pk_mul_f32 v[16:17], v[120:121], v[10:11] op_sel_hi:[1,0]
	v_add_f32_e32 v5, 1.0, v5
	v_pk_mul_f32 v[24:25], v[124:125], v[10:11] op_sel_hi:[1,0]
	v_pk_mul_f32 v[16:17], v[16:17], v[18:19]
	v_rcp_f32_e32 v18, v5
	v_add_f32_e32 v5, 1.0, v7
	v_mul_f32_e32 v7, 0xbfb8aa3b, v24
	v_exp_f32_e32 v7, v7
	v_mul_f32_e32 v9, 0xbfb8aa3b, v25
	v_exp_f32_e32 v9, v9
	v_rcp_f32_e32 v19, v5
	v_add_f32_e32 v5, 1.0, v7
	v_rcp_f32_e32 v26, v5
	v_add_f32_e32 v5, 1.0, v9
	v_rcp_f32_e32 v27, v5
	v_pk_mul_f32 v[22:23], v[114:115], v[10:11] op_sel_hi:[1,0]
	v_pk_mul_f32 v[18:19], v[20:21], v[18:19]
	v_pk_mul_f32 v[10:11], v[116:117], v[10:11] op_sel_hi:[1,0]
	v_pk_mul_f32 v[20:21], v[24:25], v[26:27]
	v_cvt_pk_bf16_f32 v14, v14, v15
	v_pk_mul_f32 v[10:11], v[10:11], v[20:21]
	v_cvt_pk_bf16_f32 v15, v16, v17
	v_cvt_pk_bf16_f32 v17, v10, v11
	v_mad_i64_i32 v[10:11], s[6:7], v12, s3, v[2:3]
	v_pk_mul_f32 v[12:13], v[110:111], v[8:9] op_sel_hi:[1,0]
	v_pk_mul_f32 v[18:19], v[22:23], v[18:19]
	v_mul_f32_e32 v5, 0xbfb8aa3b, v12
	v_exp_f32_e32 v5, v5
	v_mul_f32_e32 v7, 0xbfb8aa3b, v13
	v_exp_f32_e32 v7, v7
	v_cvt_pk_bf16_f32 v16, v18, v19
	s_waitcnt lgkmcnt(0)
; __device__ __forceinline__ unsigned pk2(float lo, float hi) { f32x2_t v = {lo, hi}; bf16x2_t b = __builtin_convertvector(v, bf16x2_t); return __builtin_bit_cast(unsigned, b); }
; __device__ __forceinline__ float sigmoidf_(float x) { return __builtin_amdgcn_rcpf(1.0f + fexp2(-x * LOG2E)); }
;     __device__ __forceinline__ void operator()(AccRef acc, const pg8::Unit& u, int wr, int wc, int fr, int fq) const {
;         const int row0 = u.pm * 256 + wr * 64 + fr, col0 = u.pn * 128 + wc * 32 + 8 * fq;
; #pragma unroll
;         for (int ai = 0; ai < 2; ++ai)
; #pragma unroll
;             for (int m = 0; m < 4; ++m) {
;                 const int row = row0 + ai * 128 + m * 16;
;                 const float rs = rst[row & 255];
;                 float v[8];
; #pragma unroll
;                 for (int n = 0; n < 2; ++n)
; #pragma unroll
;                     for (int j = 0; j < 4; ++j) { const float g = acc[ai][0][m][n][j] * rs, up = acc[ai][1][m][n][j] * rs; v[4 * n + j] = g * sigmoidf_(g) * up; }
;                 v4u w; w.x = pk2(v[0], v[1]); w.y = pk2(v[2], v[3]); w.z = pk2(v[4], v[5]); w.w = pk2(v[6], v[7]);
;                 *(v4u*)(U + (size_t)row * FF + col0) = w;
;             }
	global_store_dwordx4 v[54:55], v[48:51], off
	v_mov_b32_e32 v52, v10
	v_mov_b32_e32 v53, v11
	ds_bpermute_b32 v44, v43, v14
	ds_bpermute_b32 v45, v43, v15
	ds_bpermute_b32 v46, v43, v16
	ds_bpermute_b32 v47, v43, v17
	v_add_f32_e32 v5, 1.0, v5
	v_rcp_f32_e32 v10, v5
	v_pk_mul_f32 v[16:17], v[112:113], v[8:9] op_sel_hi:[1,0]
	v_add_f32_e32 v5, 1.0, v7
	v_mul_f32_e32 v7, 0xbfb8aa3b, v16
	v_pk_mul_f32 v[14:15], v[102:103], v[8:9] op_sel_hi:[1,0]
	v_exp_f32_e32 v7, v7
	v_mul_f32_e32 v9, 0xbfb8aa3b, v17
	v_exp_f32_e32 v9, v9
	v_rcp_f32_e32 v11, v5
	v_add_f32_e32 v5, 1.0, v7
	v_rcp_f32_e32 v18, v5
	v_add_f32_e32 v5, 1.0, v9
	v_rcp_f32_e32 v19, v5
	v_pk_mul_f32 v[10:11], v[12:13], v[10:11]
	v_pk_mul_f32 v[12:13], v[104:105], v[8:9] op_sel_hi:[1,0]
	v_pk_mul_f32 v[10:11], v[14:15], v[10:11]
	v_pk_mul_f32 v[14:15], v[16:17], v[18:19]
	v_pk_mul_f32 v[16:17], v[106:107], v[8:9] op_sel_hi:[1,0]
	v_pk_mul_f32 v[20:21], v[108:109], v[8:9] op_sel_hi:[1,0]
	v_mul_f32_e32 v5, 0xbfb8aa3b, v16
	v_exp_f32_e32 v5, v5
	v_mul_f32_e32 v7, 0xbfb8aa3b, v17
	v_exp_f32_e32 v7, v7
	v_pk_mul_f32 v[12:13], v[12:13], v[14:15]
	v_add_f32_e32 v5, 1.0, v5
	v_rcp_f32_e32 v14, v5
	v_add_f32_e32 v5, 1.0, v7
	v_mul_f32_e32 v7, 0xbfb8aa3b, v20
	v_pk_mul_f32 v[18:19], v[98:99], v[8:9] op_sel_hi:[1,0]
	v_exp_f32_e32 v7, v7
	v_mul_f32_e32 v9, 0xbfb8aa3b, v21
	v_exp_f32_e32 v9, v9
	v_rcp_f32_e32 v15, v5
	v_add_f32_e32 v5, 1.0, v7
	v_rcp_f32_e32 v22, v5
	v_add_f32_e32 v5, 1.0, v9
	v_rcp_f32_e32 v23, v5
	v_pk_mul_f32 v[14:15], v[16:17], v[14:15]
	v_pk_mul_f32 v[8:9], v[100:101], v[8:9] op_sel_hi:[1,0]
	v_pk_mul_f32 v[14:15], v[18:19], v[14:15]
	v_pk_mul_f32 v[16:17], v[20:21], v[22:23]
	s_nop 0
	v_pk_mul_f32 v[16:17], v[8:9], v[16:17]
	v_cvt_pk_bf16_f32 v8, v10, v11
	v_cvt_pk_bf16_f32 v10, v14, v15
	v_pk_mul_f32 v[14:15], v[94:95], v[6:7] op_sel_hi:[1,0]
	v_cvt_pk_bf16_f32 v9, v12, v13
	v_mul_f32_e32 v5, 0xbfb8aa3b, v14
	v_mul_f32_e32 v7, 0xbfb8aa3b, v15
	v_exp_f32_e32 v5, v5
	v_exp_f32_e32 v7, v7
	v_cvt_pk_bf16_f32 v11, v16, v17
	v_mad_i64_i32 v[12:13], s[6:7], v36, s3, v[2:3]
	s_waitcnt lgkmcnt(0)
	global_store_dwordx4 v[52:53], v[44:47], off
	v_mov_b32_e32 v54, v12
	v_mov_b32_e32 v55, v13
	ds_bpermute_b32 v48, v43, v8
	ds_bpermute_b32 v49, v43, v9
	ds_bpermute_b32 v50, v43, v10
	ds_bpermute_b32 v51, v43, v11
	v_add_f32_e32 v5, 1.0, v5
	v_pk_mul_f32 v[12:13], v[96:97], v[6:7] op_sel_hi:[1,0]
	v_rcp_f32_e32 v8, v5
	v_pk_mul_f32 v[10:11], v[86:87], v[6:7] op_sel_hi:[1,0]
	v_add_f32_e32 v5, 1.0, v7
	v_mul_f32_e32 v7, 0xbfb8aa3b, v12
	v_exp_f32_e32 v7, v7
	v_mul_f32_e32 v9, 0xbfb8aa3b, v13
	v_exp_f32_e32 v17, v9
	v_rcp_f32_e32 v9, v5
	v_add_f32_e32 v5, 1.0, v7
	v_rcp_f32_e32 v16, v5
	v_add_f32_e32 v5, 1.0, v17
	v_pk_mul_f32 v[8:9], v[14:15], v[8:9]
	v_pk_mul_f32 v[14:15], v[90:91], v[6:7] op_sel_hi:[1,0]
	v_rcp_f32_e32 v17, v5
	v_pk_mul_f32 v[8:9], v[10:11], v[8:9]
	v_pk_mul_f32 v[10:11], v[88:89], v[6:7] op_sel_hi:[1,0]
	v_mul_f32_e32 v5, 0xbfb8aa3b, v14
	v_mul_f32_e32 v7, 0xbfb8aa3b, v15
	v_exp_f32_e32 v5, v5
	v_exp_f32_e32 v7, v7
	v_pk_mul_f32 v[12:13], v[12:13], v[16:17]
	v_add_f32_e32 v5, 1.0, v5
	v_pk_mul_f32 v[18:19], v[92:93], v[6:7] op_sel_hi:[1,0]
	v_pk_mul_f32 v[10:11], v[10:11], v[12:13]
	v_rcp_f32_e32 v12, v5
	v_pk_mul_f32 v[16:17], v[82:83], v[6:7] op_sel_hi:[1,0]
	v_add_f32_e32 v5, 1.0, v7
	v_mul_f32_e32 v7, 0xbfb8aa3b, v18
	v_exp_f32_e32 v7, v7
	v_mul_f32_e32 v13, 0xbfb8aa3b, v19
	v_exp_f32_e32 v21, v13
	v_rcp_f32_e32 v13, v5
	v_add_f32_e32 v5, 1.0, v7
	v_rcp_f32_e32 v20, v5
	v_add_f32_e32 v5, 1.0, v21
	v_rcp_f32_e32 v21, v5
	v_pk_mul_f32 v[12:13], v[14:15], v[12:13]
	v_pk_mul_f32 v[6:7], v[84:85], v[6:7] op_sel_hi:[1,0]
	v_pk_mul_f32 v[12:13], v[16:17], v[12:13]
	v_pk_mul_f32 v[14:15], v[18:19], v[20:21]
	s_nop 0
	v_pk_mul_f32 v[14:15], v[6:7], v[14:15]
	v_cvt_pk_bf16_f32 v6, v8, v9
	v_cvt_pk_bf16_f32 v8, v12, v13
	v_pk_mul_f32 v[12:13], v[78:79], v[4:5] op_sel_hi:[1,0]
	v_cvt_pk_bf16_f32 v7, v10, v11
	v_cvt_pk_bf16_f32 v9, v14, v15
	v_mad_i64_i32 v[10:11], s[6:7], v37, s3, v[2:3]
	v_mul_f32_e32 v5, 0xbfb8aa3b, v12
	v_exp_f32_e32 v5, v5
	s_waitcnt lgkmcnt(0)
	global_store_dwordx4 v[54:55], v[48:51], off
	v_mov_b32_e32 v52, v10
	v_mov_b32_e32 v53, v11
	ds_bpermute_b32 v44, v43, v6
	ds_bpermute_b32 v45, v43, v7
	ds_bpermute_b32 v46, v43, v8
	ds_bpermute_b32 v47, v43, v9
	v_mad_i64_i32 v[2:3], s[6:7], v38, s3, v[2:3]
	s_nop 0
	v_mul_f32_e32 v6, 0xbfb8aa3b, v13
	v_exp_f32_e32 v7, v6
	v_add_f32_e32 v5, 1.0, v5
	v_rcp_f32_e32 v6, v5
	v_pk_mul_f32 v[8:9], v[70:71], v[4:5] op_sel_hi:[1,0]
	v_add_f32_e32 v5, 1.0, v7
	v_pk_mul_f32 v[10:11], v[80:81], v[4:5] op_sel_hi:[1,0]
	s_nop 0
	v_mul_f32_e32 v7, 0xbfb8aa3b, v10
	v_exp_f32_e32 v14, v7
	v_mul_f32_e32 v7, 0xbfb8aa3b, v11
	v_exp_f32_e32 v15, v7
	v_rcp_f32_e32 v7, v5
	v_add_f32_e32 v5, 1.0, v14
	v_rcp_f32_e32 v14, v5
	v_add_f32_e32 v5, 1.0, v15
	v_rcp_f32_e32 v15, v5
	v_pk_mul_f32 v[6:7], v[12:13], v[6:7]
	v_pk_mul_f32 v[12:13], v[74:75], v[4:5] op_sel_hi:[1,0]
	v_pk_mul_f32 v[6:7], v[8:9], v[6:7]
	v_pk_mul_f32 v[8:9], v[72:73], v[4:5] op_sel_hi:[1,0]
	v_pk_mul_f32 v[10:11], v[10:11], v[14:15]
	v_mul_f32_e32 v5, 0xbfb8aa3b, v12
	v_exp_f32_e32 v5, v5
	v_pk_mul_f32 v[8:9], v[8:9], v[10:11]
	v_mul_f32_e32 v10, 0xbfb8aa3b, v13
	v_exp_f32_e32 v11, v10
	v_add_f32_e32 v5, 1.0, v5
	v_rcp_f32_e32 v10, v5
	v_pk_mul_f32 v[14:15], v[66:67], v[4:5] op_sel_hi:[1,0]
	v_add_f32_e32 v5, 1.0, v11
	v_pk_mul_f32 v[16:17], v[76:77], v[4:5] op_sel_hi:[1,0]
	s_nop 0
	v_mul_f32_e32 v11, 0xbfb8aa3b, v16
	v_exp_f32_e32 v18, v11
	v_mul_f32_e32 v11, 0xbfb8aa3b, v17
	v_exp_f32_e32 v19, v11
	v_rcp_f32_e32 v11, v5
	v_add_f32_e32 v5, 1.0, v18
	v_rcp_f32_e32 v18, v5
	v_add_f32_e32 v5, 1.0, v19
	v_rcp_f32_e32 v19, v5
	v_pk_mul_f32 v[10:11], v[12:13], v[10:11]
	v_pk_mul_f32 v[4:5], v[68:69], v[4:5] op_sel_hi:[1,0]
	v_pk_mul_f32 v[10:11], v[14:15], v[10:11]
	v_pk_mul_f32 v[12:13], v[16:17], v[18:19]
	s_nop 0
	v_pk_mul_f32 v[12:13], v[4:5], v[12:13]
	v_cvt_pk_bf16_f32 v4, v6, v7
	v_cvt_pk_bf16_f32 v5, v8, v9
	v_cvt_pk_bf16_f32 v6, v10, v11
	v_cvt_pk_bf16_f32 v7, v12, v13
	s_waitcnt lgkmcnt(0)
	global_store_dwordx4 v[52:53], v[44:47], off
	v_mov_b32_e32 v54, v2
	v_mov_b32_e32 v55, v3
	ds_bpermute_b32 v48, v43, v4
	ds_bpermute_b32 v49, v43, v5
	ds_bpermute_b32 v50, v43, v6
	ds_bpermute_b32 v51, v43, v7
	s_waitcnt lgkmcnt(0)
	global_store_dwordx4 v[54:55], v[48:51], off
	s_andn2_b64 vcc, exec, s[96:97]
	s_cbranch_vccnz .LBB0_469
	s_branch .LBB0_378
